# v3 + P6b Hadamard lane-bit butterflies: DPP adds interleaved across the 4 values of a block (no mov_dpp/s_nop chains)
# speedup vs baseline: 1.0128x; 1.0044x over previous
.LBB0_909:
	s_waitcnt lgkmcnt(0)
	v_lshl_add_u64 v[4:5], s[8:9], 0, v[2:3]
	v_add_co_u32_e32 v24, vcc, 0x23000000, v4
	s_nop 1
	v_addc_co_u32_e32 v25, vcc, 0, v5, vcc
	global_load_dwordx2 v[86:87], v[24:25], off nt
	v_add_co_u32_e32 v54, vcc, s24, v4
	s_nop 1
	v_addc_co_u32_e32 v55, vcc, 0, v5, vcc
	v_add_co_u32_e32 v88, vcc, s25, v4
	s_nop 1
	v_addc_co_u32_e32 v89, vcc, 0, v5, vcc
	v_add_co_u32_e32 v90, vcc, s26, v4
	s_nop 1
	v_addc_co_u32_e32 v91, vcc, 0, v5, vcc
	global_load_dwordx2 v[36:37], v[54:55], off offset:1024 nt
	global_load_dwordx2 v[34:35], v[54:55], off offset:1536 nt
	global_load_dwordx2 v[32:33], v[54:55], off offset:2048 nt
	global_load_dwordx2 v[30:31], v[54:55], off offset:2560 nt
	global_load_dwordx2 v[22:23], v[88:89], off offset:512 nt
	global_load_dwordx2 v[20:21], v[88:89], off offset:1024 nt
	global_load_dwordx2 v[18:19], v[88:89], off offset:1536 nt
	global_load_dwordx2 v[16:17], v[88:89], off offset:2048 nt
	global_load_dwordx2 v[14:15], v[88:89], off offset:2560 nt
	global_load_dwordx2 v[12:13], v[88:89], off offset:3072 nt
	global_load_dwordx2 v[10:11], v[88:89], off offset:3584 nt
	global_load_dwordx2 v[28:29], v[54:55], off offset:3072 nt
	global_load_dwordx2 v[26:27], v[54:55], off offset:3584 nt
	global_load_dwordx2 v[8:9], v[90:91], off nt
	global_load_dwordx2 v[6:7], v[90:91], off offset:512 nt
	global_load_dwordx2 v[92:93], v[24:25], off offset:512 nt
	global_load_dwordx2 v[94:95], v[24:25], off offset:1024 nt
	global_load_dwordx2 v[96:97], v[24:25], off offset:1536 nt
	global_load_dwordx2 v[80:81], v[24:25], off offset:2048 nt
	global_load_dwordx2 v[78:79], v[24:25], off offset:2560 nt
	global_load_dwordx2 v[76:77], v[24:25], off offset:3072 nt
	global_load_dwordx2 v[74:75], v[24:25], off offset:3584 nt
	v_add_co_u32_e32 v56, vcc, s22, v4
	s_nop 1
	v_addc_co_u32_e32 v57, vcc, 0, v5, vcc
	v_add_co_u32_e32 v98, vcc, s23, v4
	s_nop 1
	v_addc_co_u32_e32 v99, vcc, 0, v5, vcc
	global_load_dwordx2 v[70:71], v[56:57], off offset:512 nt
	global_load_dwordx2 v[68:69], v[56:57], off offset:1024 nt
	global_load_dwordx2 v[66:67], v[56:57], off offset:1536 nt
	global_load_dwordx2 v[64:65], v[56:57], off offset:2048 nt
	global_load_dwordx2 v[62:63], v[56:57], off offset:2560 nt
	global_load_dwordx2 v[60:61], v[56:57], off offset:3072 nt
	global_load_dwordx2 v[58:59], v[56:57], off offset:3584 nt
	global_load_dwordx2 v[38:39], v[54:55], off offset:512 nt
	global_load_dwordx2 v[52:53], v[98:99], off offset:1024 nt
	global_load_dwordx2 v[50:51], v[98:99], off offset:1536 nt
	global_load_dwordx2 v[48:49], v[98:99], off offset:2048 nt
	global_load_dwordx2 v[46:47], v[98:99], off offset:2560 nt
	global_load_dwordx2 v[44:45], v[98:99], off offset:3072 nt
	global_load_dwordx2 v[42:43], v[98:99], off offset:3584 nt
	global_load_dwordx2 v[40:41], v[88:89], off offset:-4096 nt
	global_load_dwordx2 v[24:25], v[88:89], off nt
	global_load_dwordx2 v[72:73], v[98:99], off offset:-4096 nt
	global_load_dwordx2 v[56:57], v[98:99], off nt
	global_load_dwordx2 v[54:55], v[98:99], off offset:512 nt
	global_load_dwordx2 v[4:5], v[90:91], off offset:1024 nt
	s_waitcnt vmcnt(42)
	v_lshlrev_b32_e32 v88, 16, v86
	v_and_b32_e32 v86, 0xffff0000, v86
	v_lshlrev_b32_e32 v89, 16, v87
	v_and_b32_e32 v87, 0xffff0000, v87
	v_add_f32_e32 v90, v88, v86
	v_sub_f32_e32 v86, v88, v86
	v_add_f32_e32 v88, v89, v87
	v_sub_f32_e32 v87, v89, v87
	v_add_f32_e32 v89, v90, v88
	v_add_f32_e32 v91, v86, v87
	v_sub_f32_e32 v88, v90, v88
	v_sub_f32_e32 v86, v86, v87
	v_xor_b32_e32 v87, v82, v89
	v_xor_b32_e32 v90, v82, v91
	v_xor_b32_e32 v98, v82, v88
	v_add_f32_dpp v87, v89, v87 quad_perm:[1,0,3,2] row_mask:0xf bank_mask:0xf bound_ctrl:1
	v_add_f32_dpp v89, v91, v90 quad_perm:[1,0,3,2] row_mask:0xf bank_mask:0xf bound_ctrl:1
	v_xor_b32_e32 v90, v82, v86
	v_add_f32_dpp v88, v88, v98 quad_perm:[1,0,3,2] row_mask:0xf bank_mask:0xf bound_ctrl:1
	s_nop 0
	v_add_f32_dpp v86, v86, v90 quad_perm:[1,0,3,2] row_mask:0xf bank_mask:0xf bound_ctrl:1
	v_xor_b32_e32 v200, v83, v87
	v_xor_b32_e32 v201, v83, v89
	v_xor_b32_e32 v202, v83, v88
	v_xor_b32_e32 v203, v83, v86
	v_add_f32_dpp v204, v87, v200 quad_perm:[2,3,0,1] row_mask:0xf bank_mask:0xf bound_ctrl:1
	v_add_f32_dpp v205, v89, v201 quad_perm:[2,3,0,1] row_mask:0xf bank_mask:0xf bound_ctrl:1
	v_add_f32_dpp v206, v88, v202 quad_perm:[2,3,0,1] row_mask:0xf bank_mask:0xf bound_ctrl:1
	v_add_f32_dpp v207, v86, v203 quad_perm:[2,3,0,1] row_mask:0xf bank_mask:0xf bound_ctrl:1
	v_xor_b32_e32 v200, v84, v204
	v_xor_b32_e32 v201, v84, v205
	v_xor_b32_e32 v202, v84, v206
	v_xor_b32_e32 v203, v84, v207
	v_add_f32_dpp v87, v204, v200 row_shl:4 row_mask:0xf bank_mask:0x5
	v_add_f32_dpp v89, v205, v201 row_shl:4 row_mask:0xf bank_mask:0x5
	v_add_f32_dpp v88, v206, v202 row_shl:4 row_mask:0xf bank_mask:0x5
	v_add_f32_dpp v90, v207, v203 row_shl:4 row_mask:0xf bank_mask:0x5
	v_add_f32_dpp v87, v204, v200 row_shr:4 row_mask:0xf bank_mask:0xa
	v_add_f32_dpp v89, v205, v201 row_shr:4 row_mask:0xf bank_mask:0xa
	v_add_f32_dpp v88, v206, v202 row_shr:4 row_mask:0xf bank_mask:0xa
	v_add_f32_dpp v90, v207, v203 row_shr:4 row_mask:0xf bank_mask:0xa
	v_max_f32_e64 v86, |v87|, |v89|
	v_max_f32_e64 v91, |v88|, |v90|
	v_max3_f32 v91, v86, 0, v91
	v_cvt_pk_bf16_f32 v86, v87, v89
	v_cvt_pk_bf16_f32 v87, v88, v90
	s_waitcnt vmcnt(26)
	v_lshlrev_b32_e32 v88, 16, v92
	v_and_b32_e32 v89, 0xffff0000, v92
	v_lshlrev_b32_e32 v90, 16, v93
	v_and_b32_e32 v92, 0xffff0000, v93
	v_add_f32_e32 v93, v88, v89
	v_sub_f32_e32 v88, v88, v89
	v_add_f32_e32 v89, v90, v92
	v_sub_f32_e32 v90, v90, v92
	v_add_f32_e32 v92, v93, v89
	v_sub_f32_e32 v89, v93, v89
	v_add_f32_e32 v98, v88, v90
	v_sub_f32_e32 v88, v88, v90
	v_xor_b32_e32 v90, v82, v92
	v_xor_b32_e32 v93, v82, v89
	s_nop 0
	v_add_f32_dpp v90, v92, v90 quad_perm:[1,0,3,2] row_mask:0xf bank_mask:0xf bound_ctrl:1
	v_xor_b32_e32 v92, v82, v98
	v_add_f32_dpp v89, v89, v93 quad_perm:[1,0,3,2] row_mask:0xf bank_mask:0xf bound_ctrl:1
	v_xor_b32_e32 v93, v82, v88
	v_add_f32_dpp v92, v98, v92 quad_perm:[1,0,3,2] row_mask:0xf bank_mask:0xf bound_ctrl:1
	s_nop 0
	v_add_f32_dpp v88, v88, v93 quad_perm:[1,0,3,2] row_mask:0xf bank_mask:0xf bound_ctrl:1
	v_xor_b32_e32 v200, v83, v90
	v_xor_b32_e32 v201, v83, v92
	v_xor_b32_e32 v202, v83, v89
	v_xor_b32_e32 v203, v83, v88
	v_add_f32_dpp v204, v90, v200 quad_perm:[2,3,0,1] row_mask:0xf bank_mask:0xf bound_ctrl:1
	v_add_f32_dpp v205, v92, v201 quad_perm:[2,3,0,1] row_mask:0xf bank_mask:0xf bound_ctrl:1
	v_add_f32_dpp v206, v89, v202 quad_perm:[2,3,0,1] row_mask:0xf bank_mask:0xf bound_ctrl:1
	v_add_f32_dpp v207, v88, v203 quad_perm:[2,3,0,1] row_mask:0xf bank_mask:0xf bound_ctrl:1
	v_xor_b32_e32 v200, v84, v204
	v_xor_b32_e32 v201, v84, v205
	v_xor_b32_e32 v202, v84, v206
	v_xor_b32_e32 v203, v84, v207
	v_add_f32_dpp v90, v204, v200 row_shl:4 row_mask:0xf bank_mask:0x5
	v_add_f32_dpp v92, v205, v201 row_shl:4 row_mask:0xf bank_mask:0x5
	v_add_f32_dpp v89, v206, v202 row_shl:4 row_mask:0xf bank_mask:0x5
	v_add_f32_dpp v93, v207, v203 row_shl:4 row_mask:0xf bank_mask:0x5
	v_add_f32_dpp v90, v204, v200 row_shr:4 row_mask:0xf bank_mask:0xa
	v_add_f32_dpp v92, v205, v201 row_shr:4 row_mask:0xf bank_mask:0xa
	v_add_f32_dpp v89, v206, v202 row_shr:4 row_mask:0xf bank_mask:0xa
	v_add_f32_dpp v93, v207, v203 row_shr:4 row_mask:0xf bank_mask:0xa
	v_max_f32_e64 v88, |v90|, |v92|
	v_max_f32_e64 v98, |v89|, |v93|
	v_max3_f32 v91, v91, v88, v98
	v_cvt_pk_bf16_f32 v88, v90, v92
	v_cvt_pk_bf16_f32 v89, v89, v93
	s_waitcnt vmcnt(25)
	v_lshlrev_b32_e32 v90, 16, v94
	v_and_b32_e32 v92, 0xffff0000, v94
	v_lshlrev_b32_e32 v93, 16, v95
	v_and_b32_e32 v94, 0xffff0000, v95
	v_add_f32_e32 v95, v90, v92
	v_sub_f32_e32 v90, v90, v92
	v_add_f32_e32 v92, v93, v94
	v_sub_f32_e32 v93, v93, v94
	v_add_f32_e32 v94, v95, v92
	v_sub_f32_e32 v92, v95, v92
	v_add_f32_e32 v98, v90, v93
	v_sub_f32_e32 v90, v90, v93
	v_xor_b32_e32 v93, v82, v94
	v_xor_b32_e32 v95, v82, v92
	s_nop 0
	v_add_f32_dpp v93, v94, v93 quad_perm:[1,0,3,2] row_mask:0xf bank_mask:0xf bound_ctrl:1
	v_xor_b32_e32 v94, v82, v98
	v_add_f32_dpp v92, v92, v95 quad_perm:[1,0,3,2] row_mask:0xf bank_mask:0xf bound_ctrl:1
	v_xor_b32_e32 v95, v82, v90
	v_add_f32_dpp v94, v98, v94 quad_perm:[1,0,3,2] row_mask:0xf bank_mask:0xf bound_ctrl:1
	s_nop 0
	v_add_f32_dpp v90, v90, v95 quad_perm:[1,0,3,2] row_mask:0xf bank_mask:0xf bound_ctrl:1
	v_xor_b32_e32 v200, v83, v93
	v_xor_b32_e32 v201, v83, v94
	v_xor_b32_e32 v202, v83, v92
	v_xor_b32_e32 v203, v83, v90
	v_add_f32_dpp v204, v93, v200 quad_perm:[2,3,0,1] row_mask:0xf bank_mask:0xf bound_ctrl:1
	v_add_f32_dpp v205, v94, v201 quad_perm:[2,3,0,1] row_mask:0xf bank_mask:0xf bound_ctrl:1
	v_add_f32_dpp v206, v92, v202 quad_perm:[2,3,0,1] row_mask:0xf bank_mask:0xf bound_ctrl:1
	v_add_f32_dpp v207, v90, v203 quad_perm:[2,3,0,1] row_mask:0xf bank_mask:0xf bound_ctrl:1
	v_xor_b32_e32 v200, v84, v204
	v_xor_b32_e32 v201, v84, v205
	v_xor_b32_e32 v202, v84, v206
	v_xor_b32_e32 v203, v84, v207
	v_add_f32_dpp v93, v204, v200 row_shl:4 row_mask:0xf bank_mask:0x5
	v_add_f32_dpp v94, v205, v201 row_shl:4 row_mask:0xf bank_mask:0x5
	v_add_f32_dpp v92, v206, v202 row_shl:4 row_mask:0xf bank_mask:0x5
	v_add_f32_dpp v95, v207, v203 row_shl:4 row_mask:0xf bank_mask:0x5
	v_add_f32_dpp v93, v204, v200 row_shr:4 row_mask:0xf bank_mask:0xa
	v_add_f32_dpp v94, v205, v201 row_shr:4 row_mask:0xf bank_mask:0xa
	v_add_f32_dpp v92, v206, v202 row_shr:4 row_mask:0xf bank_mask:0xa
	v_add_f32_dpp v95, v207, v203 row_shr:4 row_mask:0xf bank_mask:0xa
	v_max_f32_e64 v90, |v93|, |v94|
	v_max_f32_e64 v98, |v92|, |v95|
	v_max3_f32 v98, v91, v90, v98
	v_cvt_pk_bf16_f32 v90, v93, v94
	v_cvt_pk_bf16_f32 v91, v92, v95
	s_waitcnt vmcnt(24)
	v_lshlrev_b32_e32 v92, 16, v96
	v_and_b32_e32 v93, 0xffff0000, v96
	v_lshlrev_b32_e32 v94, 16, v97
	v_and_b32_e32 v95, 0xffff0000, v97
	v_add_f32_e32 v96, v92, v93
	v_sub_f32_e32 v92, v92, v93
	v_add_f32_e32 v93, v94, v95
	v_sub_f32_e32 v94, v94, v95
	v_add_f32_e32 v95, v96, v93
	v_sub_f32_e32 v93, v96, v93
	v_add_f32_e32 v97, v92, v94
	v_sub_f32_e32 v92, v92, v94
	v_xor_b32_e32 v94, v82, v95
	v_xor_b32_e32 v96, v82, v93
	s_nop 0
	v_add_f32_dpp v94, v95, v94 quad_perm:[1,0,3,2] row_mask:0xf bank_mask:0xf bound_ctrl:1
	v_xor_b32_e32 v95, v82, v97
	v_add_f32_dpp v93, v93, v96 quad_perm:[1,0,3,2] row_mask:0xf bank_mask:0xf bound_ctrl:1
	v_xor_b32_e32 v96, v82, v92
	v_add_f32_dpp v95, v97, v95 quad_perm:[1,0,3,2] row_mask:0xf bank_mask:0xf bound_ctrl:1
	s_nop 0
	v_add_f32_dpp v92, v92, v96 quad_perm:[1,0,3,2] row_mask:0xf bank_mask:0xf bound_ctrl:1
	v_xor_b32_e32 v200, v83, v94
	v_xor_b32_e32 v201, v83, v95
	v_xor_b32_e32 v202, v83, v93
	v_xor_b32_e32 v203, v83, v92
	v_add_f32_dpp v204, v94, v200 quad_perm:[2,3,0,1] row_mask:0xf bank_mask:0xf bound_ctrl:1
	v_add_f32_dpp v205, v95, v201 quad_perm:[2,3,0,1] row_mask:0xf bank_mask:0xf bound_ctrl:1
	v_add_f32_dpp v206, v93, v202 quad_perm:[2,3,0,1] row_mask:0xf bank_mask:0xf bound_ctrl:1
	v_add_f32_dpp v207, v92, v203 quad_perm:[2,3,0,1] row_mask:0xf bank_mask:0xf bound_ctrl:1
	v_xor_b32_e32 v200, v84, v204
	v_xor_b32_e32 v201, v84, v205
	v_xor_b32_e32 v202, v84, v206
	v_xor_b32_e32 v203, v84, v207
	v_add_f32_dpp v94, v204, v200 row_shl:4 row_mask:0xf bank_mask:0x5
	v_add_f32_dpp v95, v205, v201 row_shl:4 row_mask:0xf bank_mask:0x5
	v_add_f32_dpp v93, v206, v202 row_shl:4 row_mask:0xf bank_mask:0x5
	v_add_f32_dpp v96, v207, v203 row_shl:4 row_mask:0xf bank_mask:0x5
	v_add_f32_dpp v94, v204, v200 row_shr:4 row_mask:0xf bank_mask:0xa
	v_add_f32_dpp v95, v205, v201 row_shr:4 row_mask:0xf bank_mask:0xa
	v_add_f32_dpp v93, v206, v202 row_shr:4 row_mask:0xf bank_mask:0xa
	v_add_f32_dpp v96, v207, v203 row_shr:4 row_mask:0xf bank_mask:0xa
	v_max_f32_e64 v92, |v94|, |v95|
	v_max_f32_e64 v97, |v93|, |v96|
	v_max3_f32 v97, v98, v92, v97
	v_cvt_pk_bf16_f32 v92, v94, v95
	s_waitcnt vmcnt(23)
	v_lshlrev_b32_e32 v94, 16, v80
	v_and_b32_e32 v80, 0xffff0000, v80
	v_lshlrev_b32_e32 v95, 16, v81
	v_and_b32_e32 v81, 0xffff0000, v81
	v_cvt_pk_bf16_f32 v93, v93, v96
	v_add_f32_e32 v96, v94, v80
	v_sub_f32_e32 v80, v94, v80
	v_add_f32_e32 v94, v95, v81
	v_sub_f32_e32 v81, v95, v81
	v_add_f32_e32 v95, v96, v94
	v_sub_f32_e32 v94, v96, v94
	v_add_f32_e32 v98, v80, v81
	v_sub_f32_e32 v80, v80, v81
	v_xor_b32_e32 v81, v82, v95
	v_xor_b32_e32 v96, v82, v94
	s_nop 0
	v_add_f32_dpp v81, v95, v81 quad_perm:[1,0,3,2] row_mask:0xf bank_mask:0xf bound_ctrl:1
	v_xor_b32_e32 v95, v82, v98
	v_add_f32_dpp v94, v94, v96 quad_perm:[1,0,3,2] row_mask:0xf bank_mask:0xf bound_ctrl:1
	v_xor_b32_e32 v96, v82, v80
	v_add_f32_dpp v95, v98, v95 quad_perm:[1,0,3,2] row_mask:0xf bank_mask:0xf bound_ctrl:1
	s_nop 0
	v_add_f32_dpp v80, v80, v96 quad_perm:[1,0,3,2] row_mask:0xf bank_mask:0xf bound_ctrl:1
	v_xor_b32_e32 v200, v83, v81
	v_xor_b32_e32 v201, v83, v95
	v_xor_b32_e32 v202, v83, v94
	v_xor_b32_e32 v203, v83, v80
	v_add_f32_dpp v204, v81, v200 quad_perm:[2,3,0,1] row_mask:0xf bank_mask:0xf bound_ctrl:1
	v_add_f32_dpp v205, v95, v201 quad_perm:[2,3,0,1] row_mask:0xf bank_mask:0xf bound_ctrl:1
	v_add_f32_dpp v206, v94, v202 quad_perm:[2,3,0,1] row_mask:0xf bank_mask:0xf bound_ctrl:1
	v_add_f32_dpp v207, v80, v203 quad_perm:[2,3,0,1] row_mask:0xf bank_mask:0xf bound_ctrl:1
	v_xor_b32_e32 v200, v84, v204
	v_xor_b32_e32 v201, v84, v205
	v_xor_b32_e32 v202, v84, v206
	v_xor_b32_e32 v203, v84, v207
	v_add_f32_dpp v81, v204, v200 row_shl:4 row_mask:0xf bank_mask:0x5
	v_add_f32_dpp v95, v205, v201 row_shl:4 row_mask:0xf bank_mask:0x5
	v_add_f32_dpp v94, v206, v202 row_shl:4 row_mask:0xf bank_mask:0x5
	v_add_f32_dpp v96, v207, v203 row_shl:4 row_mask:0xf bank_mask:0x5
	v_add_f32_dpp v81, v204, v200 row_shr:4 row_mask:0xf bank_mask:0xa
	v_add_f32_dpp v95, v205, v201 row_shr:4 row_mask:0xf bank_mask:0xa
	v_add_f32_dpp v94, v206, v202 row_shr:4 row_mask:0xf bank_mask:0xa
	v_add_f32_dpp v96, v207, v203 row_shr:4 row_mask:0xf bank_mask:0xa
	v_max_f32_e64 v80, |v81|, |v95|
	v_max_f32_e64 v98, |v94|, |v96|
	v_max3_f32 v97, v97, v80, v98
	v_cvt_pk_bf16_f32 v80, v81, v95
	v_cvt_pk_bf16_f32 v81, v94, v96
	s_waitcnt vmcnt(22)
	v_lshlrev_b32_e32 v94, 16, v78
	v_and_b32_e32 v78, 0xffff0000, v78
	v_lshlrev_b32_e32 v95, 16, v79
	v_and_b32_e32 v79, 0xffff0000, v79
	v_add_f32_e32 v96, v94, v78
	v_sub_f32_e32 v78, v94, v78
	v_add_f32_e32 v94, v95, v79
	v_sub_f32_e32 v79, v95, v79
	v_add_f32_e32 v95, v96, v94
	v_sub_f32_e32 v94, v96, v94
	v_add_f32_e32 v98, v78, v79
	v_sub_f32_e32 v78, v78, v79
	v_xor_b32_e32 v79, v82, v95
	v_xor_b32_e32 v96, v82, v94
	s_nop 0
	v_add_f32_dpp v79, v95, v79 quad_perm:[1,0,3,2] row_mask:0xf bank_mask:0xf bound_ctrl:1
	v_xor_b32_e32 v95, v82, v98
	v_add_f32_dpp v94, v94, v96 quad_perm:[1,0,3,2] row_mask:0xf bank_mask:0xf bound_ctrl:1
	v_xor_b32_e32 v96, v82, v78
	v_add_f32_dpp v95, v98, v95 quad_perm:[1,0,3,2] row_mask:0xf bank_mask:0xf bound_ctrl:1
	s_nop 0
	v_add_f32_dpp v78, v78, v96 quad_perm:[1,0,3,2] row_mask:0xf bank_mask:0xf bound_ctrl:1
	v_xor_b32_e32 v200, v83, v79
	v_xor_b32_e32 v201, v83, v95
	v_xor_b32_e32 v202, v83, v94
	v_xor_b32_e32 v203, v83, v78
	v_add_f32_dpp v204, v79, v200 quad_perm:[2,3,0,1] row_mask:0xf bank_mask:0xf bound_ctrl:1
	v_add_f32_dpp v205, v95, v201 quad_perm:[2,3,0,1] row_mask:0xf bank_mask:0xf bound_ctrl:1
	v_add_f32_dpp v206, v94, v202 quad_perm:[2,3,0,1] row_mask:0xf bank_mask:0xf bound_ctrl:1
	v_add_f32_dpp v207, v78, v203 quad_perm:[2,3,0,1] row_mask:0xf bank_mask:0xf bound_ctrl:1
	v_xor_b32_e32 v200, v84, v204
	v_xor_b32_e32 v201, v84, v205
	v_xor_b32_e32 v202, v84, v206
	v_xor_b32_e32 v203, v84, v207
	v_add_f32_dpp v79, v204, v200 row_shl:4 row_mask:0xf bank_mask:0x5
	v_add_f32_dpp v95, v205, v201 row_shl:4 row_mask:0xf bank_mask:0x5
	v_add_f32_dpp v94, v206, v202 row_shl:4 row_mask:0xf bank_mask:0x5
	v_add_f32_dpp v96, v207, v203 row_shl:4 row_mask:0xf bank_mask:0x5
	v_add_f32_dpp v79, v204, v200 row_shr:4 row_mask:0xf bank_mask:0xa
	v_add_f32_dpp v95, v205, v201 row_shr:4 row_mask:0xf bank_mask:0xa
	v_add_f32_dpp v94, v206, v202 row_shr:4 row_mask:0xf bank_mask:0xa
	v_add_f32_dpp v96, v207, v203 row_shr:4 row_mask:0xf bank_mask:0xa
	v_max_f32_e64 v78, |v79|, |v95|
	v_max_f32_e64 v98, |v94|, |v96|
	v_max3_f32 v97, v97, v78, v98
	v_cvt_pk_bf16_f32 v78, v79, v95
	v_cvt_pk_bf16_f32 v79, v94, v96
	s_waitcnt vmcnt(21)
	v_lshlrev_b32_e32 v94, 16, v76
	v_and_b32_e32 v76, 0xffff0000, v76
	v_lshlrev_b32_e32 v95, 16, v77
	v_and_b32_e32 v77, 0xffff0000, v77
	v_add_f32_e32 v96, v94, v76
	v_sub_f32_e32 v76, v94, v76
	v_add_f32_e32 v94, v95, v77
	v_sub_f32_e32 v77, v95, v77
	v_add_f32_e32 v95, v96, v94
	v_sub_f32_e32 v94, v96, v94
	v_add_f32_e32 v98, v76, v77
	v_sub_f32_e32 v76, v76, v77
	v_xor_b32_e32 v77, v82, v95
	v_xor_b32_e32 v96, v82, v94
	s_nop 0
	v_add_f32_dpp v77, v95, v77 quad_perm:[1,0,3,2] row_mask:0xf bank_mask:0xf bound_ctrl:1
	v_xor_b32_e32 v95, v82, v98
	v_add_f32_dpp v94, v94, v96 quad_perm:[1,0,3,2] row_mask:0xf bank_mask:0xf bound_ctrl:1
	v_xor_b32_e32 v96, v82, v76
	v_add_f32_dpp v95, v98, v95 quad_perm:[1,0,3,2] row_mask:0xf bank_mask:0xf bound_ctrl:1
	s_nop 0
	v_add_f32_dpp v76, v76, v96 quad_perm:[1,0,3,2] row_mask:0xf bank_mask:0xf bound_ctrl:1
	v_xor_b32_e32 v200, v83, v77
	v_xor_b32_e32 v201, v83, v95
	v_xor_b32_e32 v202, v83, v94
	v_xor_b32_e32 v203, v83, v76
	v_add_f32_dpp v204, v77, v200 quad_perm:[2,3,0,1] row_mask:0xf bank_mask:0xf bound_ctrl:1
	v_add_f32_dpp v205, v95, v201 quad_perm:[2,3,0,1] row_mask:0xf bank_mask:0xf bound_ctrl:1
	v_add_f32_dpp v206, v94, v202 quad_perm:[2,3,0,1] row_mask:0xf bank_mask:0xf bound_ctrl:1
	v_add_f32_dpp v207, v76, v203 quad_perm:[2,3,0,1] row_mask:0xf bank_mask:0xf bound_ctrl:1
	v_xor_b32_e32 v200, v84, v204
	v_xor_b32_e32 v201, v84, v205
	v_xor_b32_e32 v202, v84, v206
	v_xor_b32_e32 v203, v84, v207
	v_add_f32_dpp v77, v204, v200 row_shl:4 row_mask:0xf bank_mask:0x5
	v_add_f32_dpp v95, v205, v201 row_shl:4 row_mask:0xf bank_mask:0x5
	v_add_f32_dpp v94, v206, v202 row_shl:4 row_mask:0xf bank_mask:0x5
	v_add_f32_dpp v96, v207, v203 row_shl:4 row_mask:0xf bank_mask:0x5
	v_add_f32_dpp v77, v204, v200 row_shr:4 row_mask:0xf bank_mask:0xa
	v_add_f32_dpp v95, v205, v201 row_shr:4 row_mask:0xf bank_mask:0xa
	v_add_f32_dpp v94, v206, v202 row_shr:4 row_mask:0xf bank_mask:0xa
	v_add_f32_dpp v96, v207, v203 row_shr:4 row_mask:0xf bank_mask:0xa
	v_max_f32_e64 v76, |v77|, |v95|
	v_max_f32_e64 v98, |v94|, |v96|
	v_max3_f32 v97, v97, v76, v98
	v_cvt_pk_bf16_f32 v76, v77, v95
	v_cvt_pk_bf16_f32 v77, v94, v96
	s_waitcnt vmcnt(20)
	v_lshlrev_b32_e32 v94, 16, v74
	v_and_b32_e32 v74, 0xffff0000, v74
	v_lshlrev_b32_e32 v95, 16, v75
	v_and_b32_e32 v75, 0xffff0000, v75
	v_add_f32_e32 v96, v94, v74
	v_sub_f32_e32 v74, v94, v74
	v_add_f32_e32 v94, v95, v75
	v_sub_f32_e32 v75, v95, v75
	v_add_f32_e32 v95, v96, v94
	v_sub_f32_e32 v94, v96, v94
	v_add_f32_e32 v98, v74, v75
	v_sub_f32_e32 v74, v74, v75
	v_xor_b32_e32 v75, v82, v95
	v_xor_b32_e32 v96, v82, v94
	s_nop 0
	v_add_f32_dpp v75, v95, v75 quad_perm:[1,0,3,2] row_mask:0xf bank_mask:0xf bound_ctrl:1
	v_xor_b32_e32 v95, v82, v98
	v_add_f32_dpp v94, v94, v96 quad_perm:[1,0,3,2] row_mask:0xf bank_mask:0xf bound_ctrl:1
	v_xor_b32_e32 v96, v82, v74
	v_add_f32_dpp v95, v98, v95 quad_perm:[1,0,3,2] row_mask:0xf bank_mask:0xf bound_ctrl:1
	s_nop 0
	v_add_f32_dpp v74, v74, v96 quad_perm:[1,0,3,2] row_mask:0xf bank_mask:0xf bound_ctrl:1
	v_xor_b32_e32 v200, v83, v75
	v_xor_b32_e32 v201, v83, v95
	v_xor_b32_e32 v202, v83, v94
	v_xor_b32_e32 v203, v83, v74
	v_add_f32_dpp v204, v75, v200 quad_perm:[2,3,0,1] row_mask:0xf bank_mask:0xf bound_ctrl:1
	v_add_f32_dpp v205, v95, v201 quad_perm:[2,3,0,1] row_mask:0xf bank_mask:0xf bound_ctrl:1
	v_add_f32_dpp v206, v94, v202 quad_perm:[2,3,0,1] row_mask:0xf bank_mask:0xf bound_ctrl:1
	v_add_f32_dpp v207, v74, v203 quad_perm:[2,3,0,1] row_mask:0xf bank_mask:0xf bound_ctrl:1
	v_xor_b32_e32 v200, v84, v204
	v_xor_b32_e32 v201, v84, v205
	v_xor_b32_e32 v202, v84, v206
	v_xor_b32_e32 v203, v84, v207
	v_add_f32_dpp v75, v204, v200 row_shl:4 row_mask:0xf bank_mask:0x5
	v_add_f32_dpp v95, v205, v201 row_shl:4 row_mask:0xf bank_mask:0x5
	v_add_f32_dpp v94, v206, v202 row_shl:4 row_mask:0xf bank_mask:0x5
	v_add_f32_dpp v96, v207, v203 row_shl:4 row_mask:0xf bank_mask:0x5
	v_add_f32_dpp v75, v204, v200 row_shr:4 row_mask:0xf bank_mask:0xa
	v_add_f32_dpp v95, v205, v201 row_shr:4 row_mask:0xf bank_mask:0xa
	v_add_f32_dpp v94, v206, v202 row_shr:4 row_mask:0xf bank_mask:0xa
	v_add_f32_dpp v96, v207, v203 row_shr:4 row_mask:0xf bank_mask:0xa
	v_max_f32_e64 v74, |v75|, |v95|
	v_max_f32_e64 v98, |v94|, |v96|
	v_max3_f32 v97, v97, v74, v98
	v_cvt_pk_bf16_f32 v74, v75, v95
	v_cvt_pk_bf16_f32 v75, v94, v96
	s_waitcnt vmcnt(3)
	v_lshlrev_b32_e32 v94, 16, v72
	v_and_b32_e32 v72, 0xffff0000, v72
	v_lshlrev_b32_e32 v95, 16, v73
	v_and_b32_e32 v73, 0xffff0000, v73
	v_add_f32_e32 v96, v94, v72
	v_sub_f32_e32 v72, v94, v72
	v_add_f32_e32 v94, v95, v73
	v_sub_f32_e32 v73, v95, v73
	v_add_f32_e32 v95, v96, v94
	v_sub_f32_e32 v94, v96, v94
	v_add_f32_e32 v98, v72, v73
	v_sub_f32_e32 v72, v72, v73
	v_xor_b32_e32 v73, v82, v95
	v_xor_b32_e32 v96, v82, v94
	s_nop 0
	v_add_f32_dpp v73, v95, v73 quad_perm:[1,0,3,2] row_mask:0xf bank_mask:0xf bound_ctrl:1
	v_xor_b32_e32 v95, v82, v98
	v_add_f32_dpp v94, v94, v96 quad_perm:[1,0,3,2] row_mask:0xf bank_mask:0xf bound_ctrl:1
	v_xor_b32_e32 v96, v82, v72
	v_add_f32_dpp v95, v98, v95 quad_perm:[1,0,3,2] row_mask:0xf bank_mask:0xf bound_ctrl:1
	s_nop 0
	v_add_f32_dpp v72, v72, v96 quad_perm:[1,0,3,2] row_mask:0xf bank_mask:0xf bound_ctrl:1
	v_xor_b32_e32 v200, v83, v73
	v_xor_b32_e32 v201, v83, v95
	v_xor_b32_e32 v202, v83, v94
	v_xor_b32_e32 v203, v83, v72
	v_add_f32_dpp v204, v73, v200 quad_perm:[2,3,0,1] row_mask:0xf bank_mask:0xf bound_ctrl:1
	v_add_f32_dpp v205, v95, v201 quad_perm:[2,3,0,1] row_mask:0xf bank_mask:0xf bound_ctrl:1
	v_add_f32_dpp v206, v94, v202 quad_perm:[2,3,0,1] row_mask:0xf bank_mask:0xf bound_ctrl:1
	v_add_f32_dpp v207, v72, v203 quad_perm:[2,3,0,1] row_mask:0xf bank_mask:0xf bound_ctrl:1
	v_xor_b32_e32 v200, v84, v204
	v_xor_b32_e32 v201, v84, v205
	v_xor_b32_e32 v202, v84, v206
	v_xor_b32_e32 v203, v84, v207
	v_add_f32_dpp v73, v204, v200 row_shl:4 row_mask:0xf bank_mask:0x5
	v_add_f32_dpp v95, v205, v201 row_shl:4 row_mask:0xf bank_mask:0x5
	v_add_f32_dpp v94, v206, v202 row_shl:4 row_mask:0xf bank_mask:0x5
	v_add_f32_dpp v96, v207, v203 row_shl:4 row_mask:0xf bank_mask:0x5
	v_add_f32_dpp v73, v204, v200 row_shr:4 row_mask:0xf bank_mask:0xa
	v_add_f32_dpp v95, v205, v201 row_shr:4 row_mask:0xf bank_mask:0xa
	v_add_f32_dpp v94, v206, v202 row_shr:4 row_mask:0xf bank_mask:0xa
	v_add_f32_dpp v96, v207, v203 row_shr:4 row_mask:0xf bank_mask:0xa
	v_max_f32_e64 v72, |v73|, |v95|
	v_max_f32_e64 v98, |v94|, |v96|
	v_max3_f32 v97, v97, v72, v98
	v_cvt_pk_bf16_f32 v72, v73, v95
	v_cvt_pk_bf16_f32 v73, v94, v96
	v_lshlrev_b32_e32 v94, 16, v70
	v_and_b32_e32 v70, 0xffff0000, v70
	v_lshlrev_b32_e32 v95, 16, v71
	v_and_b32_e32 v71, 0xffff0000, v71
	v_add_f32_e32 v96, v94, v70
	v_sub_f32_e32 v70, v94, v70
	v_add_f32_e32 v94, v95, v71
	v_sub_f32_e32 v71, v95, v71
	v_add_f32_e32 v95, v96, v94
	v_sub_f32_e32 v94, v96, v94
	v_add_f32_e32 v98, v70, v71
	v_sub_f32_e32 v70, v70, v71
	v_xor_b32_e32 v71, v82, v95
	v_xor_b32_e32 v96, v82, v94
	s_nop 0
	v_add_f32_dpp v71, v95, v71 quad_perm:[1,0,3,2] row_mask:0xf bank_mask:0xf bound_ctrl:1
	v_xor_b32_e32 v95, v82, v98
	v_add_f32_dpp v94, v94, v96 quad_perm:[1,0,3,2] row_mask:0xf bank_mask:0xf bound_ctrl:1
	v_xor_b32_e32 v96, v82, v70
	v_add_f32_dpp v95, v98, v95 quad_perm:[1,0,3,2] row_mask:0xf bank_mask:0xf bound_ctrl:1
	s_nop 0
	v_add_f32_dpp v70, v70, v96 quad_perm:[1,0,3,2] row_mask:0xf bank_mask:0xf bound_ctrl:1
	v_xor_b32_e32 v200, v83, v71
	v_xor_b32_e32 v201, v83, v95
	v_xor_b32_e32 v202, v83, v94
	v_xor_b32_e32 v203, v83, v70
	v_add_f32_dpp v204, v71, v200 quad_perm:[2,3,0,1] row_mask:0xf bank_mask:0xf bound_ctrl:1
	v_add_f32_dpp v205, v95, v201 quad_perm:[2,3,0,1] row_mask:0xf bank_mask:0xf bound_ctrl:1
	v_add_f32_dpp v206, v94, v202 quad_perm:[2,3,0,1] row_mask:0xf bank_mask:0xf bound_ctrl:1
	v_add_f32_dpp v207, v70, v203 quad_perm:[2,3,0,1] row_mask:0xf bank_mask:0xf bound_ctrl:1
	v_xor_b32_e32 v200, v84, v204
	v_xor_b32_e32 v201, v84, v205
	v_xor_b32_e32 v202, v84, v206
	v_xor_b32_e32 v203, v84, v207
	v_add_f32_dpp v71, v204, v200 row_shl:4 row_mask:0xf bank_mask:0x5
	v_add_f32_dpp v95, v205, v201 row_shl:4 row_mask:0xf bank_mask:0x5
	v_add_f32_dpp v94, v206, v202 row_shl:4 row_mask:0xf bank_mask:0x5
	v_add_f32_dpp v96, v207, v203 row_shl:4 row_mask:0xf bank_mask:0x5
	v_add_f32_dpp v71, v204, v200 row_shr:4 row_mask:0xf bank_mask:0xa
	v_add_f32_dpp v95, v205, v201 row_shr:4 row_mask:0xf bank_mask:0xa
	v_add_f32_dpp v94, v206, v202 row_shr:4 row_mask:0xf bank_mask:0xa
	v_add_f32_dpp v96, v207, v203 row_shr:4 row_mask:0xf bank_mask:0xa
	v_max_f32_e64 v70, |v71|, |v95|
	v_max_f32_e64 v98, |v94|, |v96|
	v_max3_f32 v97, v97, v70, v98
	v_cvt_pk_bf16_f32 v70, v71, v95
	v_cvt_pk_bf16_f32 v71, v94, v96
	v_lshlrev_b32_e32 v94, 16, v68
	v_and_b32_e32 v68, 0xffff0000, v68
	v_lshlrev_b32_e32 v95, 16, v69
	v_and_b32_e32 v69, 0xffff0000, v69
	v_add_f32_e32 v96, v94, v68
	v_sub_f32_e32 v68, v94, v68
	v_add_f32_e32 v94, v95, v69
	v_sub_f32_e32 v69, v95, v69
	v_add_f32_e32 v95, v96, v94
	v_sub_f32_e32 v94, v96, v94
	v_add_f32_e32 v98, v68, v69
	v_sub_f32_e32 v68, v68, v69
	v_xor_b32_e32 v69, v82, v95
	v_xor_b32_e32 v96, v82, v94
	s_nop 0
	v_add_f32_dpp v69, v95, v69 quad_perm:[1,0,3,2] row_mask:0xf bank_mask:0xf bound_ctrl:1
	v_xor_b32_e32 v95, v82, v98
	v_add_f32_dpp v94, v94, v96 quad_perm:[1,0,3,2] row_mask:0xf bank_mask:0xf bound_ctrl:1
	v_xor_b32_e32 v96, v82, v68
	v_add_f32_dpp v95, v98, v95 quad_perm:[1,0,3,2] row_mask:0xf bank_mask:0xf bound_ctrl:1
	s_nop 0
	v_add_f32_dpp v68, v68, v96 quad_perm:[1,0,3,2] row_mask:0xf bank_mask:0xf bound_ctrl:1
	v_xor_b32_e32 v200, v83, v69
	v_xor_b32_e32 v201, v83, v95
	v_xor_b32_e32 v202, v83, v94
	v_xor_b32_e32 v203, v83, v68
	v_add_f32_dpp v204, v69, v200 quad_perm:[2,3,0,1] row_mask:0xf bank_mask:0xf bound_ctrl:1
	v_add_f32_dpp v205, v95, v201 quad_perm:[2,3,0,1] row_mask:0xf bank_mask:0xf bound_ctrl:1
	v_add_f32_dpp v206, v94, v202 quad_perm:[2,3,0,1] row_mask:0xf bank_mask:0xf bound_ctrl:1
	v_add_f32_dpp v207, v68, v203 quad_perm:[2,3,0,1] row_mask:0xf bank_mask:0xf bound_ctrl:1
	v_xor_b32_e32 v200, v84, v204
	v_xor_b32_e32 v201, v84, v205
	v_xor_b32_e32 v202, v84, v206
	v_xor_b32_e32 v203, v84, v207
	v_add_f32_dpp v69, v204, v200 row_shl:4 row_mask:0xf bank_mask:0x5
	v_add_f32_dpp v95, v205, v201 row_shl:4 row_mask:0xf bank_mask:0x5
	v_add_f32_dpp v94, v206, v202 row_shl:4 row_mask:0xf bank_mask:0x5
	v_add_f32_dpp v96, v207, v203 row_shl:4 row_mask:0xf bank_mask:0x5
	v_add_f32_dpp v69, v204, v200 row_shr:4 row_mask:0xf bank_mask:0xa
	v_add_f32_dpp v95, v205, v201 row_shr:4 row_mask:0xf bank_mask:0xa
	v_add_f32_dpp v94, v206, v202 row_shr:4 row_mask:0xf bank_mask:0xa
	v_add_f32_dpp v96, v207, v203 row_shr:4 row_mask:0xf bank_mask:0xa
	v_max_f32_e64 v68, |v69|, |v95|
	v_max_f32_e64 v98, |v94|, |v96|
	v_max3_f32 v97, v97, v68, v98
	v_cvt_pk_bf16_f32 v68, v69, v95
	v_cvt_pk_bf16_f32 v69, v94, v96
	v_lshlrev_b32_e32 v94, 16, v66
	v_and_b32_e32 v66, 0xffff0000, v66
	v_lshlrev_b32_e32 v95, 16, v67
	v_and_b32_e32 v67, 0xffff0000, v67
	v_add_f32_e32 v96, v94, v66
	v_sub_f32_e32 v66, v94, v66
	v_add_f32_e32 v94, v95, v67
	v_sub_f32_e32 v67, v95, v67
	v_add_f32_e32 v95, v96, v94
	v_sub_f32_e32 v94, v96, v94
	v_add_f32_e32 v98, v66, v67
	v_sub_f32_e32 v66, v66, v67
	v_xor_b32_e32 v67, v82, v95
	v_xor_b32_e32 v96, v82, v94
	s_nop 0
	v_add_f32_dpp v67, v95, v67 quad_perm:[1,0,3,2] row_mask:0xf bank_mask:0xf bound_ctrl:1
	v_xor_b32_e32 v95, v82, v98
	v_add_f32_dpp v94, v94, v96 quad_perm:[1,0,3,2] row_mask:0xf bank_mask:0xf bound_ctrl:1
	v_xor_b32_e32 v96, v82, v66
	v_add_f32_dpp v95, v98, v95 quad_perm:[1,0,3,2] row_mask:0xf bank_mask:0xf bound_ctrl:1
	s_nop 0
	v_add_f32_dpp v66, v66, v96 quad_perm:[1,0,3,2] row_mask:0xf bank_mask:0xf bound_ctrl:1
	v_xor_b32_e32 v200, v83, v67
	v_xor_b32_e32 v201, v83, v95
	v_xor_b32_e32 v202, v83, v94
	v_xor_b32_e32 v203, v83, v66
	v_add_f32_dpp v204, v67, v200 quad_perm:[2,3,0,1] row_mask:0xf bank_mask:0xf bound_ctrl:1
	v_add_f32_dpp v205, v95, v201 quad_perm:[2,3,0,1] row_mask:0xf bank_mask:0xf bound_ctrl:1
	v_add_f32_dpp v206, v94, v202 quad_perm:[2,3,0,1] row_mask:0xf bank_mask:0xf bound_ctrl:1
	v_add_f32_dpp v207, v66, v203 quad_perm:[2,3,0,1] row_mask:0xf bank_mask:0xf bound_ctrl:1
	v_xor_b32_e32 v200, v84, v204
	v_xor_b32_e32 v201, v84, v205
	v_xor_b32_e32 v202, v84, v206
	v_xor_b32_e32 v203, v84, v207
	v_add_f32_dpp v67, v204, v200 row_shl:4 row_mask:0xf bank_mask:0x5
	v_add_f32_dpp v95, v205, v201 row_shl:4 row_mask:0xf bank_mask:0x5
	v_add_f32_dpp v94, v206, v202 row_shl:4 row_mask:0xf bank_mask:0x5
	v_add_f32_dpp v96, v207, v203 row_shl:4 row_mask:0xf bank_mask:0x5
	v_add_f32_dpp v67, v204, v200 row_shr:4 row_mask:0xf bank_mask:0xa
	v_add_f32_dpp v95, v205, v201 row_shr:4 row_mask:0xf bank_mask:0xa
	v_add_f32_dpp v94, v206, v202 row_shr:4 row_mask:0xf bank_mask:0xa
	v_add_f32_dpp v96, v207, v203 row_shr:4 row_mask:0xf bank_mask:0xa
	v_max_f32_e64 v66, |v67|, |v95|
	v_max_f32_e64 v98, |v94|, |v96|
	v_max3_f32 v97, v97, v66, v98
	v_cvt_pk_bf16_f32 v66, v67, v95
	v_cvt_pk_bf16_f32 v67, v94, v96
	v_lshlrev_b32_e32 v94, 16, v64
	v_and_b32_e32 v64, 0xffff0000, v64
	v_lshlrev_b32_e32 v95, 16, v65
	v_and_b32_e32 v65, 0xffff0000, v65
	v_add_f32_e32 v96, v94, v64
	v_sub_f32_e32 v64, v94, v64
	v_add_f32_e32 v94, v95, v65
	v_sub_f32_e32 v65, v95, v65
	v_add_f32_e32 v95, v96, v94
	v_sub_f32_e32 v94, v96, v94
	v_add_f32_e32 v98, v64, v65
	v_sub_f32_e32 v64, v64, v65
	v_xor_b32_e32 v65, v82, v95
	v_xor_b32_e32 v96, v82, v94
	s_nop 0
	v_add_f32_dpp v65, v95, v65 quad_perm:[1,0,3,2] row_mask:0xf bank_mask:0xf bound_ctrl:1
	v_xor_b32_e32 v95, v82, v98
	v_add_f32_dpp v94, v94, v96 quad_perm:[1,0,3,2] row_mask:0xf bank_mask:0xf bound_ctrl:1
	v_xor_b32_e32 v96, v82, v64
	v_add_f32_dpp v95, v98, v95 quad_perm:[1,0,3,2] row_mask:0xf bank_mask:0xf bound_ctrl:1
	s_nop 0
	v_add_f32_dpp v64, v64, v96 quad_perm:[1,0,3,2] row_mask:0xf bank_mask:0xf bound_ctrl:1
	v_xor_b32_e32 v200, v83, v65
	v_xor_b32_e32 v201, v83, v95
	v_xor_b32_e32 v202, v83, v94
	v_xor_b32_e32 v203, v83, v64
	v_add_f32_dpp v204, v65, v200 quad_perm:[2,3,0,1] row_mask:0xf bank_mask:0xf bound_ctrl:1
	v_add_f32_dpp v205, v95, v201 quad_perm:[2,3,0,1] row_mask:0xf bank_mask:0xf bound_ctrl:1
	v_add_f32_dpp v206, v94, v202 quad_perm:[2,3,0,1] row_mask:0xf bank_mask:0xf bound_ctrl:1
	v_add_f32_dpp v207, v64, v203 quad_perm:[2,3,0,1] row_mask:0xf bank_mask:0xf bound_ctrl:1
	v_xor_b32_e32 v200, v84, v204
	v_xor_b32_e32 v201, v84, v205
	v_xor_b32_e32 v202, v84, v206
	v_xor_b32_e32 v203, v84, v207
	v_add_f32_dpp v65, v204, v200 row_shl:4 row_mask:0xf bank_mask:0x5
	v_add_f32_dpp v95, v205, v201 row_shl:4 row_mask:0xf bank_mask:0x5
	v_add_f32_dpp v94, v206, v202 row_shl:4 row_mask:0xf bank_mask:0x5
	v_add_f32_dpp v96, v207, v203 row_shl:4 row_mask:0xf bank_mask:0x5
	v_add_f32_dpp v65, v204, v200 row_shr:4 row_mask:0xf bank_mask:0xa
	v_add_f32_dpp v95, v205, v201 row_shr:4 row_mask:0xf bank_mask:0xa
	v_add_f32_dpp v94, v206, v202 row_shr:4 row_mask:0xf bank_mask:0xa
	v_add_f32_dpp v96, v207, v203 row_shr:4 row_mask:0xf bank_mask:0xa
	v_max_f32_e64 v64, |v65|, |v95|
	v_max_f32_e64 v98, |v94|, |v96|
	v_max3_f32 v97, v97, v64, v98
	v_cvt_pk_bf16_f32 v64, v65, v95
	v_cvt_pk_bf16_f32 v65, v94, v96
	v_lshlrev_b32_e32 v94, 16, v62
	v_and_b32_e32 v62, 0xffff0000, v62
	v_lshlrev_b32_e32 v95, 16, v63
	v_and_b32_e32 v63, 0xffff0000, v63
	v_add_f32_e32 v96, v94, v62
	v_sub_f32_e32 v62, v94, v62
	v_add_f32_e32 v94, v95, v63
	v_sub_f32_e32 v63, v95, v63
	v_add_f32_e32 v95, v96, v94
	v_sub_f32_e32 v94, v96, v94
	v_add_f32_e32 v98, v62, v63
	v_sub_f32_e32 v62, v62, v63
	v_xor_b32_e32 v63, v82, v95
	v_xor_b32_e32 v96, v82, v94
	s_nop 0
	v_add_f32_dpp v63, v95, v63 quad_perm:[1,0,3,2] row_mask:0xf bank_mask:0xf bound_ctrl:1
	v_xor_b32_e32 v95, v82, v98
	v_add_f32_dpp v94, v94, v96 quad_perm:[1,0,3,2] row_mask:0xf bank_mask:0xf bound_ctrl:1
	v_xor_b32_e32 v96, v82, v62
	v_add_f32_dpp v95, v98, v95 quad_perm:[1,0,3,2] row_mask:0xf bank_mask:0xf bound_ctrl:1
	s_nop 0
	v_add_f32_dpp v62, v62, v96 quad_perm:[1,0,3,2] row_mask:0xf bank_mask:0xf bound_ctrl:1
	v_xor_b32_e32 v200, v83, v63
	v_xor_b32_e32 v201, v83, v95
	v_xor_b32_e32 v202, v83, v94
	v_xor_b32_e32 v203, v83, v62
	v_add_f32_dpp v204, v63, v200 quad_perm:[2,3,0,1] row_mask:0xf bank_mask:0xf bound_ctrl:1
	v_add_f32_dpp v205, v95, v201 quad_perm:[2,3,0,1] row_mask:0xf bank_mask:0xf bound_ctrl:1
	v_add_f32_dpp v206, v94, v202 quad_perm:[2,3,0,1] row_mask:0xf bank_mask:0xf bound_ctrl:1
	v_add_f32_dpp v207, v62, v203 quad_perm:[2,3,0,1] row_mask:0xf bank_mask:0xf bound_ctrl:1
	v_xor_b32_e32 v200, v84, v204
	v_xor_b32_e32 v201, v84, v205
	v_xor_b32_e32 v202, v84, v206
	v_xor_b32_e32 v203, v84, v207
	v_add_f32_dpp v63, v204, v200 row_shl:4 row_mask:0xf bank_mask:0x5
	v_add_f32_dpp v95, v205, v201 row_shl:4 row_mask:0xf bank_mask:0x5
	v_add_f32_dpp v94, v206, v202 row_shl:4 row_mask:0xf bank_mask:0x5
	v_add_f32_dpp v96, v207, v203 row_shl:4 row_mask:0xf bank_mask:0x5
	v_add_f32_dpp v63, v204, v200 row_shr:4 row_mask:0xf bank_mask:0xa
	v_add_f32_dpp v95, v205, v201 row_shr:4 row_mask:0xf bank_mask:0xa
	v_add_f32_dpp v94, v206, v202 row_shr:4 row_mask:0xf bank_mask:0xa
	v_add_f32_dpp v96, v207, v203 row_shr:4 row_mask:0xf bank_mask:0xa
	v_max_f32_e64 v62, |v63|, |v95|
	v_max_f32_e64 v98, |v94|, |v96|
	v_max3_f32 v97, v97, v62, v98
	v_cvt_pk_bf16_f32 v62, v63, v95
	v_cvt_pk_bf16_f32 v63, v94, v96
	v_lshlrev_b32_e32 v94, 16, v60
	v_and_b32_e32 v60, 0xffff0000, v60
	v_lshlrev_b32_e32 v95, 16, v61
	v_and_b32_e32 v61, 0xffff0000, v61
	v_add_f32_e32 v96, v94, v60
	v_sub_f32_e32 v60, v94, v60
	v_add_f32_e32 v94, v95, v61
	v_sub_f32_e32 v61, v95, v61
	v_add_f32_e32 v95, v96, v94
	v_sub_f32_e32 v94, v96, v94
	v_add_f32_e32 v98, v60, v61
	v_sub_f32_e32 v60, v60, v61
	v_xor_b32_e32 v61, v82, v95
	v_xor_b32_e32 v96, v82, v94
	s_nop 0
	v_add_f32_dpp v61, v95, v61 quad_perm:[1,0,3,2] row_mask:0xf bank_mask:0xf bound_ctrl:1
	v_xor_b32_e32 v95, v82, v98
	v_add_f32_dpp v94, v94, v96 quad_perm:[1,0,3,2] row_mask:0xf bank_mask:0xf bound_ctrl:1
	v_xor_b32_e32 v96, v82, v60
	v_add_f32_dpp v95, v98, v95 quad_perm:[1,0,3,2] row_mask:0xf bank_mask:0xf bound_ctrl:1
	s_nop 0
	v_add_f32_dpp v60, v60, v96 quad_perm:[1,0,3,2] row_mask:0xf bank_mask:0xf bound_ctrl:1
	v_xor_b32_e32 v200, v83, v61
	v_xor_b32_e32 v201, v83, v95
	v_xor_b32_e32 v202, v83, v94
	v_xor_b32_e32 v203, v83, v60
	v_add_f32_dpp v204, v61, v200 quad_perm:[2,3,0,1] row_mask:0xf bank_mask:0xf bound_ctrl:1
	v_add_f32_dpp v205, v95, v201 quad_perm:[2,3,0,1] row_mask:0xf bank_mask:0xf bound_ctrl:1
	v_add_f32_dpp v206, v94, v202 quad_perm:[2,3,0,1] row_mask:0xf bank_mask:0xf bound_ctrl:1
	v_add_f32_dpp v207, v60, v203 quad_perm:[2,3,0,1] row_mask:0xf bank_mask:0xf bound_ctrl:1
	v_xor_b32_e32 v200, v84, v204
	v_xor_b32_e32 v201, v84, v205
	v_xor_b32_e32 v202, v84, v206
	v_xor_b32_e32 v203, v84, v207
	v_add_f32_dpp v61, v204, v200 row_shl:4 row_mask:0xf bank_mask:0x5
	v_add_f32_dpp v95, v205, v201 row_shl:4 row_mask:0xf bank_mask:0x5
	v_add_f32_dpp v94, v206, v202 row_shl:4 row_mask:0xf bank_mask:0x5
	v_add_f32_dpp v96, v207, v203 row_shl:4 row_mask:0xf bank_mask:0x5
	v_add_f32_dpp v61, v204, v200 row_shr:4 row_mask:0xf bank_mask:0xa
	v_add_f32_dpp v95, v205, v201 row_shr:4 row_mask:0xf bank_mask:0xa
	v_add_f32_dpp v94, v206, v202 row_shr:4 row_mask:0xf bank_mask:0xa
	v_add_f32_dpp v96, v207, v203 row_shr:4 row_mask:0xf bank_mask:0xa
	v_max_f32_e64 v60, |v61|, |v95|
	v_max_f32_e64 v98, |v94|, |v96|
	v_max3_f32 v97, v97, v60, v98
	v_cvt_pk_bf16_f32 v60, v61, v95
	v_cvt_pk_bf16_f32 v61, v94, v96
	v_lshlrev_b32_e32 v94, 16, v58
	v_and_b32_e32 v58, 0xffff0000, v58
	v_lshlrev_b32_e32 v95, 16, v59
	v_and_b32_e32 v59, 0xffff0000, v59
	v_add_f32_e32 v96, v94, v58
	v_sub_f32_e32 v58, v94, v58
	v_add_f32_e32 v94, v95, v59
	v_sub_f32_e32 v59, v95, v59
	v_add_f32_e32 v95, v96, v94
	v_sub_f32_e32 v94, v96, v94
	v_add_f32_e32 v98, v58, v59
	v_sub_f32_e32 v58, v58, v59
	v_xor_b32_e32 v59, v82, v95
	v_xor_b32_e32 v96, v82, v94
	s_nop 0
	v_add_f32_dpp v59, v95, v59 quad_perm:[1,0,3,2] row_mask:0xf bank_mask:0xf bound_ctrl:1
	v_xor_b32_e32 v95, v82, v98
	v_add_f32_dpp v94, v94, v96 quad_perm:[1,0,3,2] row_mask:0xf bank_mask:0xf bound_ctrl:1
	v_xor_b32_e32 v96, v82, v58
	v_add_f32_dpp v95, v98, v95 quad_perm:[1,0,3,2] row_mask:0xf bank_mask:0xf bound_ctrl:1
	s_nop 0
	v_add_f32_dpp v58, v58, v96 quad_perm:[1,0,3,2] row_mask:0xf bank_mask:0xf bound_ctrl:1
	v_xor_b32_e32 v200, v83, v59
	v_xor_b32_e32 v201, v83, v95
	v_xor_b32_e32 v202, v83, v94
	v_xor_b32_e32 v203, v83, v58
	v_add_f32_dpp v204, v59, v200 quad_perm:[2,3,0,1] row_mask:0xf bank_mask:0xf bound_ctrl:1
	v_add_f32_dpp v205, v95, v201 quad_perm:[2,3,0,1] row_mask:0xf bank_mask:0xf bound_ctrl:1
	v_add_f32_dpp v206, v94, v202 quad_perm:[2,3,0,1] row_mask:0xf bank_mask:0xf bound_ctrl:1
	v_add_f32_dpp v207, v58, v203 quad_perm:[2,3,0,1] row_mask:0xf bank_mask:0xf bound_ctrl:1
	v_xor_b32_e32 v200, v84, v204
	v_xor_b32_e32 v201, v84, v205
	v_xor_b32_e32 v202, v84, v206
	v_xor_b32_e32 v203, v84, v207
	v_add_f32_dpp v59, v204, v200 row_shl:4 row_mask:0xf bank_mask:0x5
	v_add_f32_dpp v95, v205, v201 row_shl:4 row_mask:0xf bank_mask:0x5
	v_add_f32_dpp v94, v206, v202 row_shl:4 row_mask:0xf bank_mask:0x5
	v_add_f32_dpp v96, v207, v203 row_shl:4 row_mask:0xf bank_mask:0x5
	v_add_f32_dpp v59, v204, v200 row_shr:4 row_mask:0xf bank_mask:0xa
	v_add_f32_dpp v95, v205, v201 row_shr:4 row_mask:0xf bank_mask:0xa
	v_add_f32_dpp v94, v206, v202 row_shr:4 row_mask:0xf bank_mask:0xa
	v_add_f32_dpp v96, v207, v203 row_shr:4 row_mask:0xf bank_mask:0xa
	v_max_f32_e64 v58, |v59|, |v95|
	v_max_f32_e64 v98, |v94|, |v96|
	v_max3_f32 v97, v97, v58, v98
	v_cvt_pk_bf16_f32 v58, v59, v95
	v_cvt_pk_bf16_f32 v59, v94, v96
	s_waitcnt vmcnt(2)
	v_lshlrev_b32_e32 v94, 16, v56
	v_and_b32_e32 v56, 0xffff0000, v56
	v_lshlrev_b32_e32 v95, 16, v57
	v_and_b32_e32 v57, 0xffff0000, v57
	v_add_f32_e32 v96, v94, v56
	v_sub_f32_e32 v56, v94, v56
	v_add_f32_e32 v94, v95, v57
	v_sub_f32_e32 v57, v95, v57
	v_add_f32_e32 v95, v96, v94
	v_sub_f32_e32 v94, v96, v94
	v_add_f32_e32 v98, v56, v57
	v_sub_f32_e32 v56, v56, v57
	v_xor_b32_e32 v57, v82, v95
	v_xor_b32_e32 v96, v82, v94
	s_nop 0
	v_add_f32_dpp v57, v95, v57 quad_perm:[1,0,3,2] row_mask:0xf bank_mask:0xf bound_ctrl:1
	v_xor_b32_e32 v95, v82, v98
	v_add_f32_dpp v94, v94, v96 quad_perm:[1,0,3,2] row_mask:0xf bank_mask:0xf bound_ctrl:1
	v_xor_b32_e32 v96, v82, v56
	v_add_f32_dpp v95, v98, v95 quad_perm:[1,0,3,2] row_mask:0xf bank_mask:0xf bound_ctrl:1
	s_nop 0
	v_add_f32_dpp v56, v56, v96 quad_perm:[1,0,3,2] row_mask:0xf bank_mask:0xf bound_ctrl:1
	v_xor_b32_e32 v200, v83, v57
	v_xor_b32_e32 v201, v83, v95
	v_xor_b32_e32 v202, v83, v94
	v_xor_b32_e32 v203, v83, v56
	v_add_f32_dpp v204, v57, v200 quad_perm:[2,3,0,1] row_mask:0xf bank_mask:0xf bound_ctrl:1
	v_add_f32_dpp v205, v95, v201 quad_perm:[2,3,0,1] row_mask:0xf bank_mask:0xf bound_ctrl:1
	v_add_f32_dpp v206, v94, v202 quad_perm:[2,3,0,1] row_mask:0xf bank_mask:0xf bound_ctrl:1
	v_add_f32_dpp v207, v56, v203 quad_perm:[2,3,0,1] row_mask:0xf bank_mask:0xf bound_ctrl:1
	v_xor_b32_e32 v200, v84, v204
	v_xor_b32_e32 v201, v84, v205
	v_xor_b32_e32 v202, v84, v206
	v_xor_b32_e32 v203, v84, v207
	v_add_f32_dpp v57, v204, v200 row_shl:4 row_mask:0xf bank_mask:0x5
	v_add_f32_dpp v95, v205, v201 row_shl:4 row_mask:0xf bank_mask:0x5
	v_add_f32_dpp v94, v206, v202 row_shl:4 row_mask:0xf bank_mask:0x5
	v_add_f32_dpp v96, v207, v203 row_shl:4 row_mask:0xf bank_mask:0x5
	v_add_f32_dpp v57, v204, v200 row_shr:4 row_mask:0xf bank_mask:0xa
	v_add_f32_dpp v95, v205, v201 row_shr:4 row_mask:0xf bank_mask:0xa
	v_add_f32_dpp v94, v206, v202 row_shr:4 row_mask:0xf bank_mask:0xa
	v_add_f32_dpp v96, v207, v203 row_shr:4 row_mask:0xf bank_mask:0xa
	v_max_f32_e64 v56, |v57|, |v95|
	v_max_f32_e64 v98, |v94|, |v96|
	v_max3_f32 v97, v97, v56, v98
	v_cvt_pk_bf16_f32 v56, v57, v95
	v_cvt_pk_bf16_f32 v57, v94, v96
	s_waitcnt vmcnt(1)
	v_lshlrev_b32_e32 v94, 16, v54
	v_and_b32_e32 v54, 0xffff0000, v54
	v_lshlrev_b32_e32 v95, 16, v55
	v_and_b32_e32 v55, 0xffff0000, v55
	v_add_f32_e32 v96, v94, v54
	v_sub_f32_e32 v54, v94, v54
	v_add_f32_e32 v94, v95, v55
	v_sub_f32_e32 v55, v95, v55
	v_add_f32_e32 v95, v96, v94
	v_sub_f32_e32 v94, v96, v94
	v_add_f32_e32 v98, v54, v55
	v_sub_f32_e32 v54, v54, v55
	v_xor_b32_e32 v55, v82, v95
	v_xor_b32_e32 v96, v82, v94
	s_nop 0
	v_add_f32_dpp v55, v95, v55 quad_perm:[1,0,3,2] row_mask:0xf bank_mask:0xf bound_ctrl:1
	v_xor_b32_e32 v95, v82, v98
	v_add_f32_dpp v94, v94, v96 quad_perm:[1,0,3,2] row_mask:0xf bank_mask:0xf bound_ctrl:1
	v_xor_b32_e32 v96, v82, v54
	v_add_f32_dpp v95, v98, v95 quad_perm:[1,0,3,2] row_mask:0xf bank_mask:0xf bound_ctrl:1
	s_nop 0
	v_add_f32_dpp v54, v54, v96 quad_perm:[1,0,3,2] row_mask:0xf bank_mask:0xf bound_ctrl:1
	v_xor_b32_e32 v200, v83, v55
	v_xor_b32_e32 v201, v83, v95
	v_xor_b32_e32 v202, v83, v94
	v_xor_b32_e32 v203, v83, v54
	v_add_f32_dpp v204, v55, v200 quad_perm:[2,3,0,1] row_mask:0xf bank_mask:0xf bound_ctrl:1
	v_add_f32_dpp v205, v95, v201 quad_perm:[2,3,0,1] row_mask:0xf bank_mask:0xf bound_ctrl:1
	v_add_f32_dpp v206, v94, v202 quad_perm:[2,3,0,1] row_mask:0xf bank_mask:0xf bound_ctrl:1
	v_add_f32_dpp v207, v54, v203 quad_perm:[2,3,0,1] row_mask:0xf bank_mask:0xf bound_ctrl:1
	v_xor_b32_e32 v200, v84, v204
	v_xor_b32_e32 v201, v84, v205
	v_xor_b32_e32 v202, v84, v206
	v_xor_b32_e32 v203, v84, v207
	v_add_f32_dpp v55, v204, v200 row_shl:4 row_mask:0xf bank_mask:0x5
	v_add_f32_dpp v95, v205, v201 row_shl:4 row_mask:0xf bank_mask:0x5
	v_add_f32_dpp v94, v206, v202 row_shl:4 row_mask:0xf bank_mask:0x5
	v_add_f32_dpp v96, v207, v203 row_shl:4 row_mask:0xf bank_mask:0x5
	v_add_f32_dpp v55, v204, v200 row_shr:4 row_mask:0xf bank_mask:0xa
	v_add_f32_dpp v95, v205, v201 row_shr:4 row_mask:0xf bank_mask:0xa
	v_add_f32_dpp v94, v206, v202 row_shr:4 row_mask:0xf bank_mask:0xa
	v_add_f32_dpp v96, v207, v203 row_shr:4 row_mask:0xf bank_mask:0xa
	v_max_f32_e64 v54, |v55|, |v95|
	v_max_f32_e64 v98, |v94|, |v96|
	v_max3_f32 v97, v97, v54, v98
	v_cvt_pk_bf16_f32 v54, v55, v95
	v_cvt_pk_bf16_f32 v55, v94, v96
	v_lshlrev_b32_e32 v94, 16, v52
	v_and_b32_e32 v52, 0xffff0000, v52
	v_lshlrev_b32_e32 v95, 16, v53
	v_and_b32_e32 v53, 0xffff0000, v53
	v_add_f32_e32 v96, v94, v52
	v_sub_f32_e32 v52, v94, v52
	v_add_f32_e32 v94, v95, v53
	v_sub_f32_e32 v53, v95, v53
	v_add_f32_e32 v95, v96, v94
	v_sub_f32_e32 v94, v96, v94
	v_add_f32_e32 v98, v52, v53
	v_sub_f32_e32 v52, v52, v53
	v_xor_b32_e32 v53, v82, v95
	v_xor_b32_e32 v96, v82, v94
	s_nop 0
	v_add_f32_dpp v53, v95, v53 quad_perm:[1,0,3,2] row_mask:0xf bank_mask:0xf bound_ctrl:1
	v_xor_b32_e32 v95, v82, v98
	v_add_f32_dpp v94, v94, v96 quad_perm:[1,0,3,2] row_mask:0xf bank_mask:0xf bound_ctrl:1
	v_xor_b32_e32 v96, v82, v52
	v_add_f32_dpp v95, v98, v95 quad_perm:[1,0,3,2] row_mask:0xf bank_mask:0xf bound_ctrl:1
	s_nop 0
	v_add_f32_dpp v52, v52, v96 quad_perm:[1,0,3,2] row_mask:0xf bank_mask:0xf bound_ctrl:1
	v_xor_b32_e32 v200, v83, v53
	v_xor_b32_e32 v201, v83, v95
	v_xor_b32_e32 v202, v83, v94
	v_xor_b32_e32 v203, v83, v52
	v_add_f32_dpp v204, v53, v200 quad_perm:[2,3,0,1] row_mask:0xf bank_mask:0xf bound_ctrl:1
	v_add_f32_dpp v205, v95, v201 quad_perm:[2,3,0,1] row_mask:0xf bank_mask:0xf bound_ctrl:1
	v_add_f32_dpp v206, v94, v202 quad_perm:[2,3,0,1] row_mask:0xf bank_mask:0xf bound_ctrl:1
	v_add_f32_dpp v207, v52, v203 quad_perm:[2,3,0,1] row_mask:0xf bank_mask:0xf bound_ctrl:1
	v_xor_b32_e32 v200, v84, v204
	v_xor_b32_e32 v201, v84, v205
	v_xor_b32_e32 v202, v84, v206
	v_xor_b32_e32 v203, v84, v207
	v_add_f32_dpp v53, v204, v200 row_shl:4 row_mask:0xf bank_mask:0x5
	v_add_f32_dpp v95, v205, v201 row_shl:4 row_mask:0xf bank_mask:0x5
	v_add_f32_dpp v94, v206, v202 row_shl:4 row_mask:0xf bank_mask:0x5
	v_add_f32_dpp v96, v207, v203 row_shl:4 row_mask:0xf bank_mask:0x5
	v_add_f32_dpp v53, v204, v200 row_shr:4 row_mask:0xf bank_mask:0xa
	v_add_f32_dpp v95, v205, v201 row_shr:4 row_mask:0xf bank_mask:0xa
	v_add_f32_dpp v94, v206, v202 row_shr:4 row_mask:0xf bank_mask:0xa
	v_add_f32_dpp v96, v207, v203 row_shr:4 row_mask:0xf bank_mask:0xa
	v_max_f32_e64 v52, |v53|, |v95|
	v_max_f32_e64 v98, |v94|, |v96|
	v_max3_f32 v97, v97, v52, v98
	v_cvt_pk_bf16_f32 v52, v53, v95
	v_cvt_pk_bf16_f32 v53, v94, v96
	v_lshlrev_b32_e32 v94, 16, v50
	v_and_b32_e32 v50, 0xffff0000, v50
	v_lshlrev_b32_e32 v95, 16, v51
	v_and_b32_e32 v51, 0xffff0000, v51
	v_add_f32_e32 v96, v94, v50
	v_sub_f32_e32 v50, v94, v50
	v_add_f32_e32 v94, v95, v51
	v_sub_f32_e32 v51, v95, v51
	v_add_f32_e32 v95, v96, v94
	v_sub_f32_e32 v94, v96, v94
	v_add_f32_e32 v98, v50, v51
	v_sub_f32_e32 v50, v50, v51
	v_xor_b32_e32 v51, v82, v95
	v_xor_b32_e32 v96, v82, v94
	s_nop 0
	v_add_f32_dpp v51, v95, v51 quad_perm:[1,0,3,2] row_mask:0xf bank_mask:0xf bound_ctrl:1
	v_xor_b32_e32 v95, v82, v98
	v_add_f32_dpp v94, v94, v96 quad_perm:[1,0,3,2] row_mask:0xf bank_mask:0xf bound_ctrl:1
	v_xor_b32_e32 v96, v82, v50
	v_add_f32_dpp v95, v98, v95 quad_perm:[1,0,3,2] row_mask:0xf bank_mask:0xf bound_ctrl:1
	s_nop 0
	v_add_f32_dpp v50, v50, v96 quad_perm:[1,0,3,2] row_mask:0xf bank_mask:0xf bound_ctrl:1
	v_xor_b32_e32 v200, v83, v51
	v_xor_b32_e32 v201, v83, v95
	v_xor_b32_e32 v202, v83, v94
	v_xor_b32_e32 v203, v83, v50
	v_add_f32_dpp v204, v51, v200 quad_perm:[2,3,0,1] row_mask:0xf bank_mask:0xf bound_ctrl:1
	v_add_f32_dpp v205, v95, v201 quad_perm:[2,3,0,1] row_mask:0xf bank_mask:0xf bound_ctrl:1
	v_add_f32_dpp v206, v94, v202 quad_perm:[2,3,0,1] row_mask:0xf bank_mask:0xf bound_ctrl:1
	v_add_f32_dpp v207, v50, v203 quad_perm:[2,3,0,1] row_mask:0xf bank_mask:0xf bound_ctrl:1
	v_xor_b32_e32 v200, v84, v204
	v_xor_b32_e32 v201, v84, v205
	v_xor_b32_e32 v202, v84, v206
	v_xor_b32_e32 v203, v84, v207
	v_add_f32_dpp v51, v204, v200 row_shl:4 row_mask:0xf bank_mask:0x5
	v_add_f32_dpp v95, v205, v201 row_shl:4 row_mask:0xf bank_mask:0x5
	v_add_f32_dpp v94, v206, v202 row_shl:4 row_mask:0xf bank_mask:0x5
	v_add_f32_dpp v96, v207, v203 row_shl:4 row_mask:0xf bank_mask:0x5
	v_add_f32_dpp v51, v204, v200 row_shr:4 row_mask:0xf bank_mask:0xa
	v_add_f32_dpp v95, v205, v201 row_shr:4 row_mask:0xf bank_mask:0xa
	v_add_f32_dpp v94, v206, v202 row_shr:4 row_mask:0xf bank_mask:0xa
	v_add_f32_dpp v96, v207, v203 row_shr:4 row_mask:0xf bank_mask:0xa
	v_max_f32_e64 v50, |v51|, |v95|
	v_max_f32_e64 v98, |v94|, |v96|
	v_max3_f32 v97, v97, v50, v98
	v_cvt_pk_bf16_f32 v50, v51, v95
	v_cvt_pk_bf16_f32 v51, v94, v96
	v_lshlrev_b32_e32 v94, 16, v48
	v_and_b32_e32 v48, 0xffff0000, v48
	v_lshlrev_b32_e32 v95, 16, v49
	v_and_b32_e32 v49, 0xffff0000, v49
	v_add_f32_e32 v96, v94, v48
	v_sub_f32_e32 v48, v94, v48
	v_add_f32_e32 v94, v95, v49
	v_sub_f32_e32 v49, v95, v49
	v_add_f32_e32 v95, v96, v94
	v_sub_f32_e32 v94, v96, v94
	v_add_f32_e32 v98, v48, v49
	v_sub_f32_e32 v48, v48, v49
	v_xor_b32_e32 v49, v82, v95
	v_xor_b32_e32 v96, v82, v94
	s_nop 0
	v_add_f32_dpp v49, v95, v49 quad_perm:[1,0,3,2] row_mask:0xf bank_mask:0xf bound_ctrl:1
	v_xor_b32_e32 v95, v82, v98
	v_add_f32_dpp v94, v94, v96 quad_perm:[1,0,3,2] row_mask:0xf bank_mask:0xf bound_ctrl:1
	v_xor_b32_e32 v96, v82, v48
	v_add_f32_dpp v95, v98, v95 quad_perm:[1,0,3,2] row_mask:0xf bank_mask:0xf bound_ctrl:1
	s_nop 0
	v_add_f32_dpp v48, v48, v96 quad_perm:[1,0,3,2] row_mask:0xf bank_mask:0xf bound_ctrl:1
	v_xor_b32_e32 v200, v83, v49
	v_xor_b32_e32 v201, v83, v95
	v_xor_b32_e32 v202, v83, v94
	v_xor_b32_e32 v203, v83, v48
	v_add_f32_dpp v204, v49, v200 quad_perm:[2,3,0,1] row_mask:0xf bank_mask:0xf bound_ctrl:1
	v_add_f32_dpp v205, v95, v201 quad_perm:[2,3,0,1] row_mask:0xf bank_mask:0xf bound_ctrl:1
	v_add_f32_dpp v206, v94, v202 quad_perm:[2,3,0,1] row_mask:0xf bank_mask:0xf bound_ctrl:1
	v_add_f32_dpp v207, v48, v203 quad_perm:[2,3,0,1] row_mask:0xf bank_mask:0xf bound_ctrl:1
	v_xor_b32_e32 v200, v84, v204
	v_xor_b32_e32 v201, v84, v205
	v_xor_b32_e32 v202, v84, v206
	v_xor_b32_e32 v203, v84, v207
	v_add_f32_dpp v49, v204, v200 row_shl:4 row_mask:0xf bank_mask:0x5
	v_add_f32_dpp v95, v205, v201 row_shl:4 row_mask:0xf bank_mask:0x5
	v_add_f32_dpp v94, v206, v202 row_shl:4 row_mask:0xf bank_mask:0x5
	v_add_f32_dpp v96, v207, v203 row_shl:4 row_mask:0xf bank_mask:0x5
	v_add_f32_dpp v49, v204, v200 row_shr:4 row_mask:0xf bank_mask:0xa
	v_add_f32_dpp v95, v205, v201 row_shr:4 row_mask:0xf bank_mask:0xa
	v_add_f32_dpp v94, v206, v202 row_shr:4 row_mask:0xf bank_mask:0xa
	v_add_f32_dpp v96, v207, v203 row_shr:4 row_mask:0xf bank_mask:0xa
	v_max_f32_e64 v48, |v49|, |v95|
	v_max_f32_e64 v98, |v94|, |v96|
	v_max3_f32 v97, v97, v48, v98
	v_cvt_pk_bf16_f32 v48, v49, v95
	v_cvt_pk_bf16_f32 v49, v94, v96
	v_lshlrev_b32_e32 v94, 16, v46
	v_and_b32_e32 v46, 0xffff0000, v46
	v_lshlrev_b32_e32 v95, 16, v47
	v_and_b32_e32 v47, 0xffff0000, v47
	v_add_f32_e32 v96, v94, v46
	v_sub_f32_e32 v46, v94, v46
	v_add_f32_e32 v94, v95, v47
	v_sub_f32_e32 v47, v95, v47
	v_add_f32_e32 v95, v96, v94
	v_sub_f32_e32 v94, v96, v94
	v_add_f32_e32 v98, v46, v47
	v_sub_f32_e32 v46, v46, v47
	v_xor_b32_e32 v47, v82, v95
	v_xor_b32_e32 v96, v82, v94
	s_nop 0
	v_add_f32_dpp v47, v95, v47 quad_perm:[1,0,3,2] row_mask:0xf bank_mask:0xf bound_ctrl:1
	v_xor_b32_e32 v95, v82, v98
	v_add_f32_dpp v94, v94, v96 quad_perm:[1,0,3,2] row_mask:0xf bank_mask:0xf bound_ctrl:1
	v_xor_b32_e32 v96, v82, v46
	v_add_f32_dpp v95, v98, v95 quad_perm:[1,0,3,2] row_mask:0xf bank_mask:0xf bound_ctrl:1
	s_nop 0
	v_add_f32_dpp v46, v46, v96 quad_perm:[1,0,3,2] row_mask:0xf bank_mask:0xf bound_ctrl:1
	v_xor_b32_e32 v200, v83, v47
	v_xor_b32_e32 v201, v83, v95
	v_xor_b32_e32 v202, v83, v94
	v_xor_b32_e32 v203, v83, v46
	v_add_f32_dpp v204, v47, v200 quad_perm:[2,3,0,1] row_mask:0xf bank_mask:0xf bound_ctrl:1
	v_add_f32_dpp v205, v95, v201 quad_perm:[2,3,0,1] row_mask:0xf bank_mask:0xf bound_ctrl:1
	v_add_f32_dpp v206, v94, v202 quad_perm:[2,3,0,1] row_mask:0xf bank_mask:0xf bound_ctrl:1
	v_add_f32_dpp v207, v46, v203 quad_perm:[2,3,0,1] row_mask:0xf bank_mask:0xf bound_ctrl:1
	v_xor_b32_e32 v200, v84, v204
	v_xor_b32_e32 v201, v84, v205
	v_xor_b32_e32 v202, v84, v206
	v_xor_b32_e32 v203, v84, v207
	v_add_f32_dpp v47, v204, v200 row_shl:4 row_mask:0xf bank_mask:0x5
	v_add_f32_dpp v95, v205, v201 row_shl:4 row_mask:0xf bank_mask:0x5
	v_add_f32_dpp v94, v206, v202 row_shl:4 row_mask:0xf bank_mask:0x5
	v_add_f32_dpp v96, v207, v203 row_shl:4 row_mask:0xf bank_mask:0x5
	v_add_f32_dpp v47, v204, v200 row_shr:4 row_mask:0xf bank_mask:0xa
	v_add_f32_dpp v95, v205, v201 row_shr:4 row_mask:0xf bank_mask:0xa
	v_add_f32_dpp v94, v206, v202 row_shr:4 row_mask:0xf bank_mask:0xa
	v_add_f32_dpp v96, v207, v203 row_shr:4 row_mask:0xf bank_mask:0xa
	v_max_f32_e64 v46, |v47|, |v95|
	v_max_f32_e64 v98, |v94|, |v96|
	v_max3_f32 v97, v97, v46, v98
	v_cvt_pk_bf16_f32 v46, v47, v95
	v_cvt_pk_bf16_f32 v47, v94, v96
	v_lshlrev_b32_e32 v94, 16, v44
	v_and_b32_e32 v44, 0xffff0000, v44
	v_lshlrev_b32_e32 v95, 16, v45
	v_and_b32_e32 v45, 0xffff0000, v45
	v_add_f32_e32 v96, v94, v44
	v_sub_f32_e32 v44, v94, v44
	v_add_f32_e32 v94, v95, v45
	v_sub_f32_e32 v45, v95, v45
	v_add_f32_e32 v95, v96, v94
	v_sub_f32_e32 v94, v96, v94
	v_add_f32_e32 v98, v44, v45
	v_sub_f32_e32 v44, v44, v45
	v_xor_b32_e32 v45, v82, v95
	v_xor_b32_e32 v96, v82, v94
	s_nop 0
	v_add_f32_dpp v45, v95, v45 quad_perm:[1,0,3,2] row_mask:0xf bank_mask:0xf bound_ctrl:1
	v_xor_b32_e32 v95, v82, v98
	v_add_f32_dpp v94, v94, v96 quad_perm:[1,0,3,2] row_mask:0xf bank_mask:0xf bound_ctrl:1
	v_xor_b32_e32 v96, v82, v44
	v_add_f32_dpp v95, v98, v95 quad_perm:[1,0,3,2] row_mask:0xf bank_mask:0xf bound_ctrl:1
	s_nop 0
	v_add_f32_dpp v44, v44, v96 quad_perm:[1,0,3,2] row_mask:0xf bank_mask:0xf bound_ctrl:1
	v_xor_b32_e32 v200, v83, v45
	v_xor_b32_e32 v201, v83, v95
	v_xor_b32_e32 v202, v83, v94
	v_xor_b32_e32 v203, v83, v44
	v_add_f32_dpp v204, v45, v200 quad_perm:[2,3,0,1] row_mask:0xf bank_mask:0xf bound_ctrl:1
	v_add_f32_dpp v205, v95, v201 quad_perm:[2,3,0,1] row_mask:0xf bank_mask:0xf bound_ctrl:1
	v_add_f32_dpp v206, v94, v202 quad_perm:[2,3,0,1] row_mask:0xf bank_mask:0xf bound_ctrl:1
	v_add_f32_dpp v207, v44, v203 quad_perm:[2,3,0,1] row_mask:0xf bank_mask:0xf bound_ctrl:1
	v_xor_b32_e32 v200, v84, v204
	v_xor_b32_e32 v201, v84, v205
	v_xor_b32_e32 v202, v84, v206
	v_xor_b32_e32 v203, v84, v207
	v_add_f32_dpp v45, v204, v200 row_shl:4 row_mask:0xf bank_mask:0x5
	v_add_f32_dpp v95, v205, v201 row_shl:4 row_mask:0xf bank_mask:0x5
	v_add_f32_dpp v94, v206, v202 row_shl:4 row_mask:0xf bank_mask:0x5
	v_add_f32_dpp v96, v207, v203 row_shl:4 row_mask:0xf bank_mask:0x5
	v_add_f32_dpp v45, v204, v200 row_shr:4 row_mask:0xf bank_mask:0xa
	v_add_f32_dpp v95, v205, v201 row_shr:4 row_mask:0xf bank_mask:0xa
	v_add_f32_dpp v94, v206, v202 row_shr:4 row_mask:0xf bank_mask:0xa
	v_add_f32_dpp v96, v207, v203 row_shr:4 row_mask:0xf bank_mask:0xa
	v_max_f32_e64 v44, |v45|, |v95|
	v_max_f32_e64 v98, |v94|, |v96|
	v_max3_f32 v97, v97, v44, v98
	v_cvt_pk_bf16_f32 v44, v45, v95
	v_cvt_pk_bf16_f32 v45, v94, v96
	v_lshlrev_b32_e32 v94, 16, v42
	v_and_b32_e32 v42, 0xffff0000, v42
	v_lshlrev_b32_e32 v95, 16, v43
	v_and_b32_e32 v43, 0xffff0000, v43
	v_add_f32_e32 v96, v94, v42
	v_sub_f32_e32 v42, v94, v42
	v_add_f32_e32 v94, v95, v43
	v_sub_f32_e32 v43, v95, v43
	v_add_f32_e32 v95, v96, v94
	v_sub_f32_e32 v94, v96, v94
	v_add_f32_e32 v98, v42, v43
	v_sub_f32_e32 v42, v42, v43
	v_xor_b32_e32 v43, v82, v95
	v_xor_b32_e32 v96, v82, v94
	s_nop 0
	v_add_f32_dpp v43, v95, v43 quad_perm:[1,0,3,2] row_mask:0xf bank_mask:0xf bound_ctrl:1
	v_xor_b32_e32 v95, v82, v98
	v_add_f32_dpp v94, v94, v96 quad_perm:[1,0,3,2] row_mask:0xf bank_mask:0xf bound_ctrl:1
	v_xor_b32_e32 v96, v82, v42
	v_add_f32_dpp v95, v98, v95 quad_perm:[1,0,3,2] row_mask:0xf bank_mask:0xf bound_ctrl:1
	s_nop 0
	v_add_f32_dpp v42, v42, v96 quad_perm:[1,0,3,2] row_mask:0xf bank_mask:0xf bound_ctrl:1
	v_xor_b32_e32 v200, v83, v43
	v_xor_b32_e32 v201, v83, v95
	v_xor_b32_e32 v202, v83, v94
	v_xor_b32_e32 v203, v83, v42
	v_add_f32_dpp v204, v43, v200 quad_perm:[2,3,0,1] row_mask:0xf bank_mask:0xf bound_ctrl:1
	v_add_f32_dpp v205, v95, v201 quad_perm:[2,3,0,1] row_mask:0xf bank_mask:0xf bound_ctrl:1
	v_add_f32_dpp v206, v94, v202 quad_perm:[2,3,0,1] row_mask:0xf bank_mask:0xf bound_ctrl:1
	v_add_f32_dpp v207, v42, v203 quad_perm:[2,3,0,1] row_mask:0xf bank_mask:0xf bound_ctrl:1
	v_xor_b32_e32 v200, v84, v204
	v_xor_b32_e32 v201, v84, v205
	v_xor_b32_e32 v202, v84, v206
	v_xor_b32_e32 v203, v84, v207
	v_add_f32_dpp v43, v204, v200 row_shl:4 row_mask:0xf bank_mask:0x5
	v_add_f32_dpp v95, v205, v201 row_shl:4 row_mask:0xf bank_mask:0x5
	v_add_f32_dpp v94, v206, v202 row_shl:4 row_mask:0xf bank_mask:0x5
	v_add_f32_dpp v96, v207, v203 row_shl:4 row_mask:0xf bank_mask:0x5
	v_add_f32_dpp v43, v204, v200 row_shr:4 row_mask:0xf bank_mask:0xa
	v_add_f32_dpp v95, v205, v201 row_shr:4 row_mask:0xf bank_mask:0xa
	v_add_f32_dpp v94, v206, v202 row_shr:4 row_mask:0xf bank_mask:0xa
	v_add_f32_dpp v96, v207, v203 row_shr:4 row_mask:0xf bank_mask:0xa
	v_max_f32_e64 v42, |v43|, |v95|
	v_max_f32_e64 v98, |v94|, |v96|
	v_max3_f32 v97, v97, v42, v98
	v_cvt_pk_bf16_f32 v42, v43, v95
	v_cvt_pk_bf16_f32 v43, v94, v96
	v_lshlrev_b32_e32 v94, 16, v40
	v_and_b32_e32 v40, 0xffff0000, v40
	v_lshlrev_b32_e32 v95, 16, v41
	v_and_b32_e32 v41, 0xffff0000, v41
	v_add_f32_e32 v96, v94, v40
	v_sub_f32_e32 v40, v94, v40
	v_add_f32_e32 v94, v95, v41
	v_sub_f32_e32 v41, v95, v41
	v_add_f32_e32 v95, v96, v94
	v_sub_f32_e32 v94, v96, v94
	v_add_f32_e32 v98, v40, v41
	v_sub_f32_e32 v40, v40, v41
	v_xor_b32_e32 v41, v82, v95
	v_xor_b32_e32 v96, v82, v94
	s_nop 0
	v_add_f32_dpp v41, v95, v41 quad_perm:[1,0,3,2] row_mask:0xf bank_mask:0xf bound_ctrl:1
	v_xor_b32_e32 v95, v82, v98
	v_add_f32_dpp v94, v94, v96 quad_perm:[1,0,3,2] row_mask:0xf bank_mask:0xf bound_ctrl:1
	v_xor_b32_e32 v96, v82, v40
	v_add_f32_dpp v95, v98, v95 quad_perm:[1,0,3,2] row_mask:0xf bank_mask:0xf bound_ctrl:1
	s_nop 0
	v_add_f32_dpp v40, v40, v96 quad_perm:[1,0,3,2] row_mask:0xf bank_mask:0xf bound_ctrl:1
	v_xor_b32_e32 v200, v83, v41
	v_xor_b32_e32 v201, v83, v95
	v_xor_b32_e32 v202, v83, v94
	v_xor_b32_e32 v203, v83, v40
	v_add_f32_dpp v204, v41, v200 quad_perm:[2,3,0,1] row_mask:0xf bank_mask:0xf bound_ctrl:1
	v_add_f32_dpp v205, v95, v201 quad_perm:[2,3,0,1] row_mask:0xf bank_mask:0xf bound_ctrl:1
	v_add_f32_dpp v206, v94, v202 quad_perm:[2,3,0,1] row_mask:0xf bank_mask:0xf bound_ctrl:1
	v_add_f32_dpp v207, v40, v203 quad_perm:[2,3,0,1] row_mask:0xf bank_mask:0xf bound_ctrl:1
	v_xor_b32_e32 v200, v84, v204
	v_xor_b32_e32 v201, v84, v205
	v_xor_b32_e32 v202, v84, v206
	v_xor_b32_e32 v203, v84, v207
	v_add_f32_dpp v41, v204, v200 row_shl:4 row_mask:0xf bank_mask:0x5
	v_add_f32_dpp v95, v205, v201 row_shl:4 row_mask:0xf bank_mask:0x5
	v_add_f32_dpp v94, v206, v202 row_shl:4 row_mask:0xf bank_mask:0x5
	v_add_f32_dpp v96, v207, v203 row_shl:4 row_mask:0xf bank_mask:0x5
	v_add_f32_dpp v41, v204, v200 row_shr:4 row_mask:0xf bank_mask:0xa
	v_add_f32_dpp v95, v205, v201 row_shr:4 row_mask:0xf bank_mask:0xa
	v_add_f32_dpp v94, v206, v202 row_shr:4 row_mask:0xf bank_mask:0xa
	v_add_f32_dpp v96, v207, v203 row_shr:4 row_mask:0xf bank_mask:0xa
	v_max_f32_e64 v40, |v41|, |v95|
	v_max_f32_e64 v98, |v94|, |v96|
	v_max3_f32 v97, v97, v40, v98
	v_cvt_pk_bf16_f32 v40, v41, v95
	v_cvt_pk_bf16_f32 v41, v94, v96
	v_lshlrev_b32_e32 v94, 16, v38
	v_and_b32_e32 v38, 0xffff0000, v38
	v_lshlrev_b32_e32 v95, 16, v39
	v_and_b32_e32 v39, 0xffff0000, v39
	v_add_f32_e32 v96, v94, v38
	v_sub_f32_e32 v38, v94, v38
	v_add_f32_e32 v94, v95, v39
	v_sub_f32_e32 v39, v95, v39
	v_add_f32_e32 v95, v96, v94
	v_sub_f32_e32 v94, v96, v94
	v_add_f32_e32 v98, v38, v39
	v_sub_f32_e32 v38, v38, v39
	v_xor_b32_e32 v39, v82, v95
	v_xor_b32_e32 v96, v82, v94
	s_nop 0
	v_add_f32_dpp v39, v95, v39 quad_perm:[1,0,3,2] row_mask:0xf bank_mask:0xf bound_ctrl:1
	v_xor_b32_e32 v95, v82, v98
	v_add_f32_dpp v94, v94, v96 quad_perm:[1,0,3,2] row_mask:0xf bank_mask:0xf bound_ctrl:1
	v_xor_b32_e32 v96, v82, v38
	v_add_f32_dpp v95, v98, v95 quad_perm:[1,0,3,2] row_mask:0xf bank_mask:0xf bound_ctrl:1
	s_nop 0
	v_add_f32_dpp v38, v38, v96 quad_perm:[1,0,3,2] row_mask:0xf bank_mask:0xf bound_ctrl:1
	v_xor_b32_e32 v200, v83, v39
	v_xor_b32_e32 v201, v83, v95
	v_xor_b32_e32 v202, v83, v94
	v_xor_b32_e32 v203, v83, v38
	v_add_f32_dpp v204, v39, v200 quad_perm:[2,3,0,1] row_mask:0xf bank_mask:0xf bound_ctrl:1
	v_add_f32_dpp v205, v95, v201 quad_perm:[2,3,0,1] row_mask:0xf bank_mask:0xf bound_ctrl:1
	v_add_f32_dpp v206, v94, v202 quad_perm:[2,3,0,1] row_mask:0xf bank_mask:0xf bound_ctrl:1
	v_add_f32_dpp v207, v38, v203 quad_perm:[2,3,0,1] row_mask:0xf bank_mask:0xf bound_ctrl:1
	v_xor_b32_e32 v200, v84, v204
	v_xor_b32_e32 v201, v84, v205
	v_xor_b32_e32 v202, v84, v206
	v_xor_b32_e32 v203, v84, v207
	v_add_f32_dpp v39, v204, v200 row_shl:4 row_mask:0xf bank_mask:0x5
	v_add_f32_dpp v95, v205, v201 row_shl:4 row_mask:0xf bank_mask:0x5
	v_add_f32_dpp v94, v206, v202 row_shl:4 row_mask:0xf bank_mask:0x5
	v_add_f32_dpp v96, v207, v203 row_shl:4 row_mask:0xf bank_mask:0x5
	v_add_f32_dpp v39, v204, v200 row_shr:4 row_mask:0xf bank_mask:0xa
	v_add_f32_dpp v95, v205, v201 row_shr:4 row_mask:0xf bank_mask:0xa
	v_add_f32_dpp v94, v206, v202 row_shr:4 row_mask:0xf bank_mask:0xa
	v_add_f32_dpp v96, v207, v203 row_shr:4 row_mask:0xf bank_mask:0xa
	v_max_f32_e64 v38, |v39|, |v95|
	v_max_f32_e64 v98, |v94|, |v96|
	v_max3_f32 v97, v97, v38, v98
	v_cvt_pk_bf16_f32 v38, v39, v95
	v_cvt_pk_bf16_f32 v39, v94, v96
	v_lshlrev_b32_e32 v94, 16, v36
	v_and_b32_e32 v36, 0xffff0000, v36
	v_lshlrev_b32_e32 v95, 16, v37
	v_and_b32_e32 v37, 0xffff0000, v37
	v_add_f32_e32 v96, v94, v36
	v_sub_f32_e32 v36, v94, v36
	v_add_f32_e32 v94, v95, v37
	v_sub_f32_e32 v37, v95, v37
	v_add_f32_e32 v95, v96, v94
	v_sub_f32_e32 v94, v96, v94
	v_add_f32_e32 v98, v36, v37
	v_sub_f32_e32 v36, v36, v37
	v_xor_b32_e32 v37, v82, v95
	v_xor_b32_e32 v96, v82, v94
	s_nop 0
	v_add_f32_dpp v37, v95, v37 quad_perm:[1,0,3,2] row_mask:0xf bank_mask:0xf bound_ctrl:1
	v_xor_b32_e32 v95, v82, v98
	v_add_f32_dpp v94, v94, v96 quad_perm:[1,0,3,2] row_mask:0xf bank_mask:0xf bound_ctrl:1
	v_xor_b32_e32 v96, v82, v36
	v_add_f32_dpp v95, v98, v95 quad_perm:[1,0,3,2] row_mask:0xf bank_mask:0xf bound_ctrl:1
	s_nop 0
	v_add_f32_dpp v36, v36, v96 quad_perm:[1,0,3,2] row_mask:0xf bank_mask:0xf bound_ctrl:1
	v_xor_b32_e32 v200, v83, v37
	v_xor_b32_e32 v201, v83, v95
	v_xor_b32_e32 v202, v83, v94
	v_xor_b32_e32 v203, v83, v36
	v_add_f32_dpp v204, v37, v200 quad_perm:[2,3,0,1] row_mask:0xf bank_mask:0xf bound_ctrl:1
	v_add_f32_dpp v205, v95, v201 quad_perm:[2,3,0,1] row_mask:0xf bank_mask:0xf bound_ctrl:1
	v_add_f32_dpp v206, v94, v202 quad_perm:[2,3,0,1] row_mask:0xf bank_mask:0xf bound_ctrl:1
	v_add_f32_dpp v207, v36, v203 quad_perm:[2,3,0,1] row_mask:0xf bank_mask:0xf bound_ctrl:1
	v_xor_b32_e32 v200, v84, v204
	v_xor_b32_e32 v201, v84, v205
	v_xor_b32_e32 v202, v84, v206
	v_xor_b32_e32 v203, v84, v207
	v_add_f32_dpp v37, v204, v200 row_shl:4 row_mask:0xf bank_mask:0x5
	v_add_f32_dpp v95, v205, v201 row_shl:4 row_mask:0xf bank_mask:0x5
	v_add_f32_dpp v94, v206, v202 row_shl:4 row_mask:0xf bank_mask:0x5
	v_add_f32_dpp v96, v207, v203 row_shl:4 row_mask:0xf bank_mask:0x5
	v_add_f32_dpp v37, v204, v200 row_shr:4 row_mask:0xf bank_mask:0xa
	v_add_f32_dpp v95, v205, v201 row_shr:4 row_mask:0xf bank_mask:0xa
	v_add_f32_dpp v94, v206, v202 row_shr:4 row_mask:0xf bank_mask:0xa
	v_add_f32_dpp v96, v207, v203 row_shr:4 row_mask:0xf bank_mask:0xa
	v_max_f32_e64 v36, |v37|, |v95|
	v_max_f32_e64 v98, |v94|, |v96|
	v_max3_f32 v97, v97, v36, v98
	v_cvt_pk_bf16_f32 v36, v37, v95
	v_cvt_pk_bf16_f32 v37, v94, v96
	v_lshlrev_b32_e32 v94, 16, v34
	v_and_b32_e32 v34, 0xffff0000, v34
	v_lshlrev_b32_e32 v95, 16, v35
	v_and_b32_e32 v35, 0xffff0000, v35
	v_add_f32_e32 v96, v94, v34
	v_sub_f32_e32 v34, v94, v34
	v_add_f32_e32 v94, v95, v35
	v_sub_f32_e32 v35, v95, v35
	v_add_f32_e32 v95, v96, v94
	v_sub_f32_e32 v94, v96, v94
	v_add_f32_e32 v98, v34, v35
	v_sub_f32_e32 v34, v34, v35
	v_xor_b32_e32 v35, v82, v95
	v_xor_b32_e32 v96, v82, v94
	s_nop 0
	v_add_f32_dpp v35, v95, v35 quad_perm:[1,0,3,2] row_mask:0xf bank_mask:0xf bound_ctrl:1
	v_xor_b32_e32 v95, v82, v98
	v_add_f32_dpp v94, v94, v96 quad_perm:[1,0,3,2] row_mask:0xf bank_mask:0xf bound_ctrl:1
	v_xor_b32_e32 v96, v82, v34
	v_add_f32_dpp v95, v98, v95 quad_perm:[1,0,3,2] row_mask:0xf bank_mask:0xf bound_ctrl:1
	s_nop 0
	v_add_f32_dpp v34, v34, v96 quad_perm:[1,0,3,2] row_mask:0xf bank_mask:0xf bound_ctrl:1
	v_xor_b32_e32 v200, v83, v35
	v_xor_b32_e32 v201, v83, v95
	v_xor_b32_e32 v202, v83, v94
	v_xor_b32_e32 v203, v83, v34
	v_add_f32_dpp v204, v35, v200 quad_perm:[2,3,0,1] row_mask:0xf bank_mask:0xf bound_ctrl:1
	v_add_f32_dpp v205, v95, v201 quad_perm:[2,3,0,1] row_mask:0xf bank_mask:0xf bound_ctrl:1
	v_add_f32_dpp v206, v94, v202 quad_perm:[2,3,0,1] row_mask:0xf bank_mask:0xf bound_ctrl:1
	v_add_f32_dpp v207, v34, v203 quad_perm:[2,3,0,1] row_mask:0xf bank_mask:0xf bound_ctrl:1
	v_xor_b32_e32 v200, v84, v204
	v_xor_b32_e32 v201, v84, v205
	v_xor_b32_e32 v202, v84, v206
	v_xor_b32_e32 v203, v84, v207
	v_add_f32_dpp v35, v204, v200 row_shl:4 row_mask:0xf bank_mask:0x5
	v_add_f32_dpp v95, v205, v201 row_shl:4 row_mask:0xf bank_mask:0x5
	v_add_f32_dpp v94, v206, v202 row_shl:4 row_mask:0xf bank_mask:0x5
	v_add_f32_dpp v96, v207, v203 row_shl:4 row_mask:0xf bank_mask:0x5
	v_add_f32_dpp v35, v204, v200 row_shr:4 row_mask:0xf bank_mask:0xa
	v_add_f32_dpp v95, v205, v201 row_shr:4 row_mask:0xf bank_mask:0xa
	v_add_f32_dpp v94, v206, v202 row_shr:4 row_mask:0xf bank_mask:0xa
	v_add_f32_dpp v96, v207, v203 row_shr:4 row_mask:0xf bank_mask:0xa
	v_max_f32_e64 v34, |v35|, |v95|
	v_max_f32_e64 v98, |v94|, |v96|
	v_max3_f32 v97, v97, v34, v98
	v_cvt_pk_bf16_f32 v34, v35, v95
	v_cvt_pk_bf16_f32 v35, v94, v96
	v_lshlrev_b32_e32 v94, 16, v32
	v_and_b32_e32 v32, 0xffff0000, v32
	v_lshlrev_b32_e32 v95, 16, v33
	v_and_b32_e32 v33, 0xffff0000, v33
	v_add_f32_e32 v96, v94, v32
	v_sub_f32_e32 v32, v94, v32
	v_add_f32_e32 v94, v95, v33
	v_sub_f32_e32 v33, v95, v33
	v_add_f32_e32 v95, v96, v94
	v_sub_f32_e32 v94, v96, v94
	v_add_f32_e32 v98, v32, v33
	v_sub_f32_e32 v32, v32, v33
	v_xor_b32_e32 v33, v82, v95
	v_xor_b32_e32 v96, v82, v94
	s_nop 0
	v_add_f32_dpp v33, v95, v33 quad_perm:[1,0,3,2] row_mask:0xf bank_mask:0xf bound_ctrl:1
	v_xor_b32_e32 v95, v82, v98
	v_add_f32_dpp v94, v94, v96 quad_perm:[1,0,3,2] row_mask:0xf bank_mask:0xf bound_ctrl:1
	v_xor_b32_e32 v96, v82, v32
	v_add_f32_dpp v95, v98, v95 quad_perm:[1,0,3,2] row_mask:0xf bank_mask:0xf bound_ctrl:1
	s_nop 0
	v_add_f32_dpp v32, v32, v96 quad_perm:[1,0,3,2] row_mask:0xf bank_mask:0xf bound_ctrl:1
	v_xor_b32_e32 v200, v83, v33
	v_xor_b32_e32 v201, v83, v95
	v_xor_b32_e32 v202, v83, v94
	v_xor_b32_e32 v203, v83, v32
	v_add_f32_dpp v204, v33, v200 quad_perm:[2,3,0,1] row_mask:0xf bank_mask:0xf bound_ctrl:1
	v_add_f32_dpp v205, v95, v201 quad_perm:[2,3,0,1] row_mask:0xf bank_mask:0xf bound_ctrl:1
	v_add_f32_dpp v206, v94, v202 quad_perm:[2,3,0,1] row_mask:0xf bank_mask:0xf bound_ctrl:1
	v_add_f32_dpp v207, v32, v203 quad_perm:[2,3,0,1] row_mask:0xf bank_mask:0xf bound_ctrl:1
	v_xor_b32_e32 v200, v84, v204
	v_xor_b32_e32 v201, v84, v205
	v_xor_b32_e32 v202, v84, v206
	v_xor_b32_e32 v203, v84, v207
	v_add_f32_dpp v33, v204, v200 row_shl:4 row_mask:0xf bank_mask:0x5
	v_add_f32_dpp v95, v205, v201 row_shl:4 row_mask:0xf bank_mask:0x5
	v_add_f32_dpp v94, v206, v202 row_shl:4 row_mask:0xf bank_mask:0x5
	v_add_f32_dpp v96, v207, v203 row_shl:4 row_mask:0xf bank_mask:0x5
	v_add_f32_dpp v33, v204, v200 row_shr:4 row_mask:0xf bank_mask:0xa
	v_add_f32_dpp v95, v205, v201 row_shr:4 row_mask:0xf bank_mask:0xa
	v_add_f32_dpp v94, v206, v202 row_shr:4 row_mask:0xf bank_mask:0xa
	v_add_f32_dpp v96, v207, v203 row_shr:4 row_mask:0xf bank_mask:0xa
	v_max_f32_e64 v32, |v33|, |v95|
	v_max_f32_e64 v98, |v94|, |v96|
	v_max3_f32 v97, v97, v32, v98
	v_cvt_pk_bf16_f32 v32, v33, v95
	v_cvt_pk_bf16_f32 v33, v94, v96
	v_lshlrev_b32_e32 v94, 16, v30
	v_and_b32_e32 v30, 0xffff0000, v30
	v_lshlrev_b32_e32 v95, 16, v31
	v_and_b32_e32 v31, 0xffff0000, v31
	v_add_f32_e32 v96, v94, v30
	v_sub_f32_e32 v30, v94, v30
	v_add_f32_e32 v94, v95, v31
	v_sub_f32_e32 v31, v95, v31
	v_add_f32_e32 v95, v96, v94
	v_sub_f32_e32 v94, v96, v94
	v_add_f32_e32 v98, v30, v31
	v_sub_f32_e32 v30, v30, v31
	v_xor_b32_e32 v31, v82, v95
	v_xor_b32_e32 v96, v82, v94
	s_nop 0
	v_add_f32_dpp v31, v95, v31 quad_perm:[1,0,3,2] row_mask:0xf bank_mask:0xf bound_ctrl:1
	v_xor_b32_e32 v95, v82, v98
	v_add_f32_dpp v94, v94, v96 quad_perm:[1,0,3,2] row_mask:0xf bank_mask:0xf bound_ctrl:1
	v_xor_b32_e32 v96, v82, v30
	v_add_f32_dpp v95, v98, v95 quad_perm:[1,0,3,2] row_mask:0xf bank_mask:0xf bound_ctrl:1
	s_nop 0
	v_add_f32_dpp v30, v30, v96 quad_perm:[1,0,3,2] row_mask:0xf bank_mask:0xf bound_ctrl:1
	v_xor_b32_e32 v200, v83, v31
	v_xor_b32_e32 v201, v83, v95
	v_xor_b32_e32 v202, v83, v94
	v_xor_b32_e32 v203, v83, v30
	v_add_f32_dpp v204, v31, v200 quad_perm:[2,3,0,1] row_mask:0xf bank_mask:0xf bound_ctrl:1
	v_add_f32_dpp v205, v95, v201 quad_perm:[2,3,0,1] row_mask:0xf bank_mask:0xf bound_ctrl:1
	v_add_f32_dpp v206, v94, v202 quad_perm:[2,3,0,1] row_mask:0xf bank_mask:0xf bound_ctrl:1
	v_add_f32_dpp v207, v30, v203 quad_perm:[2,3,0,1] row_mask:0xf bank_mask:0xf bound_ctrl:1
	v_xor_b32_e32 v200, v84, v204
	v_xor_b32_e32 v201, v84, v205
	v_xor_b32_e32 v202, v84, v206
	v_xor_b32_e32 v203, v84, v207
	v_add_f32_dpp v31, v204, v200 row_shl:4 row_mask:0xf bank_mask:0x5
	v_add_f32_dpp v95, v205, v201 row_shl:4 row_mask:0xf bank_mask:0x5
	v_add_f32_dpp v94, v206, v202 row_shl:4 row_mask:0xf bank_mask:0x5
	v_add_f32_dpp v96, v207, v203 row_shl:4 row_mask:0xf bank_mask:0x5
	v_add_f32_dpp v31, v204, v200 row_shr:4 row_mask:0xf bank_mask:0xa
	v_add_f32_dpp v95, v205, v201 row_shr:4 row_mask:0xf bank_mask:0xa
	v_add_f32_dpp v94, v206, v202 row_shr:4 row_mask:0xf bank_mask:0xa
	v_add_f32_dpp v96, v207, v203 row_shr:4 row_mask:0xf bank_mask:0xa
	v_max_f32_e64 v30, |v31|, |v95|
	v_max_f32_e64 v98, |v94|, |v96|
	v_max3_f32 v97, v97, v30, v98
	v_cvt_pk_bf16_f32 v30, v31, v95
	v_cvt_pk_bf16_f32 v31, v94, v96
	v_lshlrev_b32_e32 v94, 16, v28
	v_and_b32_e32 v28, 0xffff0000, v28
	v_lshlrev_b32_e32 v95, 16, v29
	v_and_b32_e32 v29, 0xffff0000, v29
	v_add_f32_e32 v96, v94, v28
	v_sub_f32_e32 v28, v94, v28
	v_add_f32_e32 v94, v95, v29
	v_sub_f32_e32 v29, v95, v29
	v_add_f32_e32 v95, v96, v94
	v_sub_f32_e32 v94, v96, v94
	v_add_f32_e32 v98, v28, v29
	v_sub_f32_e32 v28, v28, v29
	v_xor_b32_e32 v29, v82, v95
	v_xor_b32_e32 v96, v82, v94
	s_nop 0
	v_add_f32_dpp v29, v95, v29 quad_perm:[1,0,3,2] row_mask:0xf bank_mask:0xf bound_ctrl:1
	v_xor_b32_e32 v95, v82, v98
	v_add_f32_dpp v94, v94, v96 quad_perm:[1,0,3,2] row_mask:0xf bank_mask:0xf bound_ctrl:1
	v_xor_b32_e32 v96, v82, v28
	v_add_f32_dpp v95, v98, v95 quad_perm:[1,0,3,2] row_mask:0xf bank_mask:0xf bound_ctrl:1
	s_nop 0
	v_add_f32_dpp v28, v28, v96 quad_perm:[1,0,3,2] row_mask:0xf bank_mask:0xf bound_ctrl:1
	v_xor_b32_e32 v200, v83, v29
	v_xor_b32_e32 v201, v83, v95
	v_xor_b32_e32 v202, v83, v94
	v_xor_b32_e32 v203, v83, v28
	v_add_f32_dpp v204, v29, v200 quad_perm:[2,3,0,1] row_mask:0xf bank_mask:0xf bound_ctrl:1
	v_add_f32_dpp v205, v95, v201 quad_perm:[2,3,0,1] row_mask:0xf bank_mask:0xf bound_ctrl:1
	v_add_f32_dpp v206, v94, v202 quad_perm:[2,3,0,1] row_mask:0xf bank_mask:0xf bound_ctrl:1
	v_add_f32_dpp v207, v28, v203 quad_perm:[2,3,0,1] row_mask:0xf bank_mask:0xf bound_ctrl:1
	v_xor_b32_e32 v200, v84, v204
	v_xor_b32_e32 v201, v84, v205
	v_xor_b32_e32 v202, v84, v206
	v_xor_b32_e32 v203, v84, v207
	v_add_f32_dpp v29, v204, v200 row_shl:4 row_mask:0xf bank_mask:0x5
	v_add_f32_dpp v95, v205, v201 row_shl:4 row_mask:0xf bank_mask:0x5
	v_add_f32_dpp v94, v206, v202 row_shl:4 row_mask:0xf bank_mask:0x5
	v_add_f32_dpp v96, v207, v203 row_shl:4 row_mask:0xf bank_mask:0x5
	v_add_f32_dpp v29, v204, v200 row_shr:4 row_mask:0xf bank_mask:0xa
	v_add_f32_dpp v95, v205, v201 row_shr:4 row_mask:0xf bank_mask:0xa
	v_add_f32_dpp v94, v206, v202 row_shr:4 row_mask:0xf bank_mask:0xa
	v_add_f32_dpp v96, v207, v203 row_shr:4 row_mask:0xf bank_mask:0xa
	v_max_f32_e64 v28, |v29|, |v95|
	v_max_f32_e64 v98, |v94|, |v96|
	v_max3_f32 v97, v97, v28, v98
	v_cvt_pk_bf16_f32 v28, v29, v95
	v_cvt_pk_bf16_f32 v29, v94, v96
	v_lshlrev_b32_e32 v94, 16, v26
	v_and_b32_e32 v26, 0xffff0000, v26
	v_lshlrev_b32_e32 v95, 16, v27
	v_and_b32_e32 v27, 0xffff0000, v27
	v_add_f32_e32 v96, v94, v26
	v_sub_f32_e32 v26, v94, v26
	v_add_f32_e32 v94, v95, v27
	v_sub_f32_e32 v27, v95, v27
	v_add_f32_e32 v95, v96, v94
	v_sub_f32_e32 v94, v96, v94
	v_add_f32_e32 v98, v26, v27
	v_sub_f32_e32 v26, v26, v27
	v_xor_b32_e32 v27, v82, v95
	v_xor_b32_e32 v96, v82, v94
	s_nop 0
	v_add_f32_dpp v27, v95, v27 quad_perm:[1,0,3,2] row_mask:0xf bank_mask:0xf bound_ctrl:1
	v_xor_b32_e32 v95, v82, v98
	v_add_f32_dpp v94, v94, v96 quad_perm:[1,0,3,2] row_mask:0xf bank_mask:0xf bound_ctrl:1
	v_xor_b32_e32 v96, v82, v26
	v_add_f32_dpp v95, v98, v95 quad_perm:[1,0,3,2] row_mask:0xf bank_mask:0xf bound_ctrl:1
	s_nop 0
	v_add_f32_dpp v26, v26, v96 quad_perm:[1,0,3,2] row_mask:0xf bank_mask:0xf bound_ctrl:1
	v_xor_b32_e32 v200, v83, v27
	v_xor_b32_e32 v201, v83, v95
	v_xor_b32_e32 v202, v83, v94
	v_xor_b32_e32 v203, v83, v26
	v_add_f32_dpp v204, v27, v200 quad_perm:[2,3,0,1] row_mask:0xf bank_mask:0xf bound_ctrl:1
	v_add_f32_dpp v205, v95, v201 quad_perm:[2,3,0,1] row_mask:0xf bank_mask:0xf bound_ctrl:1
	v_add_f32_dpp v206, v94, v202 quad_perm:[2,3,0,1] row_mask:0xf bank_mask:0xf bound_ctrl:1
	v_add_f32_dpp v207, v26, v203 quad_perm:[2,3,0,1] row_mask:0xf bank_mask:0xf bound_ctrl:1
	v_xor_b32_e32 v200, v84, v204
	v_xor_b32_e32 v201, v84, v205
	v_xor_b32_e32 v202, v84, v206
	v_xor_b32_e32 v203, v84, v207
	v_add_f32_dpp v27, v204, v200 row_shl:4 row_mask:0xf bank_mask:0x5
	v_add_f32_dpp v95, v205, v201 row_shl:4 row_mask:0xf bank_mask:0x5
	v_add_f32_dpp v94, v206, v202 row_shl:4 row_mask:0xf bank_mask:0x5
	v_add_f32_dpp v96, v207, v203 row_shl:4 row_mask:0xf bank_mask:0x5
	v_add_f32_dpp v27, v204, v200 row_shr:4 row_mask:0xf bank_mask:0xa
	v_add_f32_dpp v95, v205, v201 row_shr:4 row_mask:0xf bank_mask:0xa
	v_add_f32_dpp v94, v206, v202 row_shr:4 row_mask:0xf bank_mask:0xa
	v_add_f32_dpp v96, v207, v203 row_shr:4 row_mask:0xf bank_mask:0xa
	v_max_f32_e64 v26, |v27|, |v95|
	v_max_f32_e64 v98, |v94|, |v96|
	v_max3_f32 v97, v97, v26, v98
	v_cvt_pk_bf16_f32 v26, v27, v95
	v_cvt_pk_bf16_f32 v27, v94, v96
	v_lshlrev_b32_e32 v94, 16, v24
	v_and_b32_e32 v24, 0xffff0000, v24
	v_lshlrev_b32_e32 v95, 16, v25
	v_and_b32_e32 v25, 0xffff0000, v25
	v_add_f32_e32 v96, v94, v24
	v_sub_f32_e32 v24, v94, v24
	v_add_f32_e32 v94, v95, v25
	v_sub_f32_e32 v25, v95, v25
	v_add_f32_e32 v95, v96, v94
	v_sub_f32_e32 v94, v96, v94
	v_add_f32_e32 v98, v24, v25
	v_sub_f32_e32 v24, v24, v25
	v_xor_b32_e32 v25, v82, v95
	v_xor_b32_e32 v96, v82, v94
	s_nop 0
	v_add_f32_dpp v25, v95, v25 quad_perm:[1,0,3,2] row_mask:0xf bank_mask:0xf bound_ctrl:1
	v_xor_b32_e32 v95, v82, v98
	v_add_f32_dpp v94, v94, v96 quad_perm:[1,0,3,2] row_mask:0xf bank_mask:0xf bound_ctrl:1
	v_xor_b32_e32 v96, v82, v24
	v_add_f32_dpp v95, v98, v95 quad_perm:[1,0,3,2] row_mask:0xf bank_mask:0xf bound_ctrl:1
	s_nop 0
	v_add_f32_dpp v24, v24, v96 quad_perm:[1,0,3,2] row_mask:0xf bank_mask:0xf bound_ctrl:1
	v_xor_b32_e32 v200, v83, v25
	v_xor_b32_e32 v201, v83, v95
	v_xor_b32_e32 v202, v83, v94
	v_xor_b32_e32 v203, v83, v24
	v_add_f32_dpp v204, v25, v200 quad_perm:[2,3,0,1] row_mask:0xf bank_mask:0xf bound_ctrl:1
	v_add_f32_dpp v205, v95, v201 quad_perm:[2,3,0,1] row_mask:0xf bank_mask:0xf bound_ctrl:1
	v_add_f32_dpp v206, v94, v202 quad_perm:[2,3,0,1] row_mask:0xf bank_mask:0xf bound_ctrl:1
	v_add_f32_dpp v207, v24, v203 quad_perm:[2,3,0,1] row_mask:0xf bank_mask:0xf bound_ctrl:1
	v_xor_b32_e32 v200, v84, v204
	v_xor_b32_e32 v201, v84, v205
	v_xor_b32_e32 v202, v84, v206
	v_xor_b32_e32 v203, v84, v207
	v_add_f32_dpp v24, v204, v200 row_shl:4 row_mask:0xf bank_mask:0x5
	v_add_f32_dpp v25, v205, v201 row_shl:4 row_mask:0xf bank_mask:0x5
	v_add_f32_dpp v94, v206, v202 row_shl:4 row_mask:0xf bank_mask:0x5
	v_add_f32_dpp v95, v207, v203 row_shl:4 row_mask:0xf bank_mask:0x5
	v_add_f32_dpp v24, v204, v200 row_shr:4 row_mask:0xf bank_mask:0xa
	v_add_f32_dpp v25, v205, v201 row_shr:4 row_mask:0xf bank_mask:0xa
	v_add_f32_dpp v94, v206, v202 row_shr:4 row_mask:0xf bank_mask:0xa
	v_add_f32_dpp v95, v207, v203 row_shr:4 row_mask:0xf bank_mask:0xa
	v_max_f32_e64 v96, |v24|, |v25|
	v_max_f32_e64 v98, |v94|, |v95|
	v_max3_f32 v98, v97, v96, v98
	v_lshlrev_b32_e32 v96, 16, v22
	v_and_b32_e32 v22, 0xffff0000, v22
	v_lshlrev_b32_e32 v97, 16, v23
	v_and_b32_e32 v23, 0xffff0000, v23
	v_add_f32_e32 v99, v96, v22
	v_sub_f32_e32 v22, v96, v22
	v_add_f32_e32 v96, v97, v23
	v_sub_f32_e32 v23, v97, v23
	v_add_f32_e32 v97, v99, v96
	v_sub_f32_e32 v96, v99, v96
	v_add_f32_e32 v100, v22, v23
	v_sub_f32_e32 v22, v22, v23
	v_xor_b32_e32 v23, v82, v97
	v_xor_b32_e32 v99, v82, v96
	v_cvt_pk_bf16_f32 v24, v24, v25
	v_cvt_pk_bf16_f32 v25, v94, v95
	s_nop 0
	v_add_f32_dpp v23, v97, v23 quad_perm:[1,0,3,2] row_mask:0xf bank_mask:0xf bound_ctrl:1
	v_xor_b32_e32 v97, v82, v100
	v_add_f32_dpp v96, v96, v99 quad_perm:[1,0,3,2] row_mask:0xf bank_mask:0xf bound_ctrl:1
	v_xor_b32_e32 v99, v82, v22
	v_add_f32_dpp v97, v100, v97 quad_perm:[1,0,3,2] row_mask:0xf bank_mask:0xf bound_ctrl:1
	s_nop 0
	v_add_f32_dpp v22, v22, v99 quad_perm:[1,0,3,2] row_mask:0xf bank_mask:0xf bound_ctrl:1
	v_xor_b32_e32 v200, v83, v23
	v_xor_b32_e32 v201, v83, v97
	v_xor_b32_e32 v202, v83, v96
	v_xor_b32_e32 v203, v83, v22
	v_add_f32_dpp v204, v23, v200 quad_perm:[2,3,0,1] row_mask:0xf bank_mask:0xf bound_ctrl:1
	v_add_f32_dpp v205, v97, v201 quad_perm:[2,3,0,1] row_mask:0xf bank_mask:0xf bound_ctrl:1
	v_add_f32_dpp v206, v96, v202 quad_perm:[2,3,0,1] row_mask:0xf bank_mask:0xf bound_ctrl:1
	v_add_f32_dpp v207, v22, v203 quad_perm:[2,3,0,1] row_mask:0xf bank_mask:0xf bound_ctrl:1
	v_xor_b32_e32 v200, v84, v204
	v_xor_b32_e32 v201, v84, v205
	v_xor_b32_e32 v202, v84, v206
	v_xor_b32_e32 v203, v84, v207
	v_add_f32_dpp v22, v204, v200 row_shl:4 row_mask:0xf bank_mask:0x5
	v_add_f32_dpp v23, v205, v201 row_shl:4 row_mask:0xf bank_mask:0x5
	v_add_f32_dpp v96, v206, v202 row_shl:4 row_mask:0xf bank_mask:0x5
	v_add_f32_dpp v97, v207, v203 row_shl:4 row_mask:0xf bank_mask:0x5
	v_add_f32_dpp v22, v204, v200 row_shr:4 row_mask:0xf bank_mask:0xa
	v_add_f32_dpp v23, v205, v201 row_shr:4 row_mask:0xf bank_mask:0xa
	v_add_f32_dpp v96, v206, v202 row_shr:4 row_mask:0xf bank_mask:0xa
	v_add_f32_dpp v97, v207, v203 row_shr:4 row_mask:0xf bank_mask:0xa
	v_max_f32_e64 v99, |v22|, |v23|
	v_max_f32_e64 v100, |v96|, |v97|
	v_max3_f32 v98, v98, v99, v100
	v_lshlrev_b32_e32 v99, 16, v20
	v_and_b32_e32 v20, 0xffff0000, v20
	v_lshlrev_b32_e32 v100, 16, v21
	v_and_b32_e32 v21, 0xffff0000, v21
	v_add_f32_e32 v101, v99, v20
	v_sub_f32_e32 v20, v99, v20
	v_add_f32_e32 v99, v100, v21
	v_sub_f32_e32 v21, v100, v21
	v_add_f32_e32 v100, v101, v99
	v_sub_f32_e32 v99, v101, v99
	v_add_f32_e32 v102, v20, v21
	v_sub_f32_e32 v20, v20, v21
	v_xor_b32_e32 v21, v82, v100
	v_xor_b32_e32 v101, v82, v99
	v_cvt_pk_bf16_f32 v22, v22, v23
	v_cvt_pk_bf16_f32 v23, v96, v97
	s_nop 0
	v_add_f32_dpp v21, v100, v21 quad_perm:[1,0,3,2] row_mask:0xf bank_mask:0xf bound_ctrl:1
	v_xor_b32_e32 v100, v82, v102
	v_add_f32_dpp v99, v99, v101 quad_perm:[1,0,3,2] row_mask:0xf bank_mask:0xf bound_ctrl:1
	v_xor_b32_e32 v101, v82, v20
	v_add_f32_dpp v100, v102, v100 quad_perm:[1,0,3,2] row_mask:0xf bank_mask:0xf bound_ctrl:1
	s_nop 0
	v_add_f32_dpp v20, v20, v101 quad_perm:[1,0,3,2] row_mask:0xf bank_mask:0xf bound_ctrl:1
	v_xor_b32_e32 v200, v83, v21
	v_xor_b32_e32 v201, v83, v100
	v_xor_b32_e32 v202, v83, v99
	v_xor_b32_e32 v203, v83, v20
	v_add_f32_dpp v204, v21, v200 quad_perm:[2,3,0,1] row_mask:0xf bank_mask:0xf bound_ctrl:1
	v_add_f32_dpp v205, v100, v201 quad_perm:[2,3,0,1] row_mask:0xf bank_mask:0xf bound_ctrl:1
	v_add_f32_dpp v206, v99, v202 quad_perm:[2,3,0,1] row_mask:0xf bank_mask:0xf bound_ctrl:1
	v_add_f32_dpp v207, v20, v203 quad_perm:[2,3,0,1] row_mask:0xf bank_mask:0xf bound_ctrl:1
	v_xor_b32_e32 v200, v84, v204
	v_xor_b32_e32 v201, v84, v205
	v_xor_b32_e32 v202, v84, v206
	v_xor_b32_e32 v203, v84, v207
	v_add_f32_dpp v21, v204, v200 row_shl:4 row_mask:0xf bank_mask:0x5
	v_add_f32_dpp v100, v205, v201 row_shl:4 row_mask:0xf bank_mask:0x5
	v_add_f32_dpp v99, v206, v202 row_shl:4 row_mask:0xf bank_mask:0x5
	v_add_f32_dpp v20, v207, v203 row_shl:4 row_mask:0xf bank_mask:0x5
	v_add_f32_dpp v21, v204, v200 row_shr:4 row_mask:0xf bank_mask:0xa
	v_add_f32_dpp v100, v205, v201 row_shr:4 row_mask:0xf bank_mask:0xa
	v_add_f32_dpp v99, v206, v202 row_shr:4 row_mask:0xf bank_mask:0xa
	v_add_f32_dpp v20, v207, v203 row_shr:4 row_mask:0xf bank_mask:0xa
	v_cvt_pk_bf16_f32 v96, v21, v100
	v_max_f32_e64 v101, |v21|, |v100|
	v_max_f32_e64 v102, |v99|, |v20|
	v_max3_f32 v98, v98, v101, v102
	v_lshlrev_b32_e32 v101, 16, v18
	v_and_b32_e32 v18, 0xffff0000, v18
	v_lshlrev_b32_e32 v102, 16, v19
	v_and_b32_e32 v19, 0xffff0000, v19
	v_add_f32_e32 v103, v101, v18
	v_sub_f32_e32 v18, v101, v18
	v_add_f32_e32 v101, v102, v19
	v_sub_f32_e32 v19, v102, v19
	v_add_f32_e32 v102, v103, v101
	v_sub_f32_e32 v101, v103, v101
	v_add_f32_e32 v104, v18, v19
	v_sub_f32_e32 v18, v18, v19
	v_xor_b32_e32 v19, v82, v102
	v_xor_b32_e32 v103, v82, v101
	v_cvt_pk_bf16_f32 v97, v99, v20
	s_nop 0
	v_add_f32_dpp v19, v102, v19 quad_perm:[1,0,3,2] row_mask:0xf bank_mask:0xf bound_ctrl:1
	v_xor_b32_e32 v102, v82, v104
	v_add_f32_dpp v101, v101, v103 quad_perm:[1,0,3,2] row_mask:0xf bank_mask:0xf bound_ctrl:1
	v_xor_b32_e32 v103, v82, v18
	v_add_f32_dpp v102, v104, v102 quad_perm:[1,0,3,2] row_mask:0xf bank_mask:0xf bound_ctrl:1
	s_nop 0
	v_add_f32_dpp v18, v18, v103 quad_perm:[1,0,3,2] row_mask:0xf bank_mask:0xf bound_ctrl:1
	v_xor_b32_e32 v200, v83, v19
	v_xor_b32_e32 v201, v83, v102
	v_xor_b32_e32 v202, v83, v101
	v_xor_b32_e32 v203, v83, v18
	v_add_f32_dpp v204, v19, v200 quad_perm:[2,3,0,1] row_mask:0xf bank_mask:0xf bound_ctrl:1
	v_add_f32_dpp v205, v102, v201 quad_perm:[2,3,0,1] row_mask:0xf bank_mask:0xf bound_ctrl:1
	v_add_f32_dpp v206, v101, v202 quad_perm:[2,3,0,1] row_mask:0xf bank_mask:0xf bound_ctrl:1
	v_add_f32_dpp v207, v18, v203 quad_perm:[2,3,0,1] row_mask:0xf bank_mask:0xf bound_ctrl:1
	v_xor_b32_e32 v200, v84, v204
	v_xor_b32_e32 v201, v84, v205
	v_xor_b32_e32 v202, v84, v206
	v_xor_b32_e32 v203, v84, v207
	v_add_f32_dpp v19, v204, v200 row_shl:4 row_mask:0xf bank_mask:0x5
	v_add_f32_dpp v102, v205, v201 row_shl:4 row_mask:0xf bank_mask:0x5
	v_add_f32_dpp v101, v206, v202 row_shl:4 row_mask:0xf bank_mask:0x5
	v_add_f32_dpp v18, v207, v203 row_shl:4 row_mask:0xf bank_mask:0x5
	v_add_f32_dpp v19, v204, v200 row_shr:4 row_mask:0xf bank_mask:0xa
	v_add_f32_dpp v102, v205, v201 row_shr:4 row_mask:0xf bank_mask:0xa
	v_add_f32_dpp v101, v206, v202 row_shr:4 row_mask:0xf bank_mask:0xa
	v_add_f32_dpp v18, v207, v203 row_shr:4 row_mask:0xf bank_mask:0xa
	v_max_f32_e64 v103, |v19|, |v102|
	v_max_f32_e64 v104, |v101|, |v18|
	v_max3_f32 v98, v98, v103, v104
	v_lshlrev_b32_e32 v103, 16, v16
	v_and_b32_e32 v16, 0xffff0000, v16
	v_lshlrev_b32_e32 v104, 16, v17
	v_and_b32_e32 v17, 0xffff0000, v17
	v_add_f32_e32 v105, v103, v16
	v_sub_f32_e32 v16, v103, v16
	v_add_f32_e32 v103, v104, v17
	v_sub_f32_e32 v17, v104, v17
	v_add_f32_e32 v104, v105, v103
	v_sub_f32_e32 v103, v105, v103
	v_add_f32_e32 v106, v16, v17
	v_sub_f32_e32 v16, v16, v17
	v_xor_b32_e32 v17, v82, v104
	v_xor_b32_e32 v105, v82, v103
	v_cvt_pk_bf16_f32 v19, v19, v102
	s_nop 0
	v_add_f32_dpp v17, v104, v17 quad_perm:[1,0,3,2] row_mask:0xf bank_mask:0xf bound_ctrl:1
	v_xor_b32_e32 v104, v82, v106
	v_add_f32_dpp v103, v103, v105 quad_perm:[1,0,3,2] row_mask:0xf bank_mask:0xf bound_ctrl:1
	v_xor_b32_e32 v105, v82, v16
	v_add_f32_dpp v104, v106, v104 quad_perm:[1,0,3,2] row_mask:0xf bank_mask:0xf bound_ctrl:1
	s_nop 0
	v_add_f32_dpp v16, v16, v105 quad_perm:[1,0,3,2] row_mask:0xf bank_mask:0xf bound_ctrl:1
	v_xor_b32_e32 v200, v83, v17
	v_xor_b32_e32 v201, v83, v104
	v_xor_b32_e32 v202, v83, v103
	v_xor_b32_e32 v203, v83, v16
	v_add_f32_dpp v204, v17, v200 quad_perm:[2,3,0,1] row_mask:0xf bank_mask:0xf bound_ctrl:1
	v_add_f32_dpp v205, v104, v201 quad_perm:[2,3,0,1] row_mask:0xf bank_mask:0xf bound_ctrl:1
	v_add_f32_dpp v206, v103, v202 quad_perm:[2,3,0,1] row_mask:0xf bank_mask:0xf bound_ctrl:1
	v_add_f32_dpp v207, v16, v203 quad_perm:[2,3,0,1] row_mask:0xf bank_mask:0xf bound_ctrl:1
	v_xor_b32_e32 v200, v84, v204
	v_xor_b32_e32 v201, v84, v205
	v_xor_b32_e32 v202, v84, v206
	v_xor_b32_e32 v203, v84, v207
	v_add_f32_dpp v17, v204, v200 row_shl:4 row_mask:0xf bank_mask:0x5
	v_add_f32_dpp v104, v205, v201 row_shl:4 row_mask:0xf bank_mask:0x5
	v_add_f32_dpp v103, v206, v202 row_shl:4 row_mask:0xf bank_mask:0x5
	v_add_f32_dpp v16, v207, v203 row_shl:4 row_mask:0xf bank_mask:0x5
	v_add_f32_dpp v17, v204, v200 row_shr:4 row_mask:0xf bank_mask:0xa
	v_add_f32_dpp v104, v205, v201 row_shr:4 row_mask:0xf bank_mask:0xa
	v_add_f32_dpp v103, v206, v202 row_shr:4 row_mask:0xf bank_mask:0xa
	v_add_f32_dpp v16, v207, v203 row_shr:4 row_mask:0xf bank_mask:0xa
	v_max_f32_e64 v105, |v17|, |v104|
	v_max_f32_e64 v106, |v103|, |v16|
	v_max3_f32 v98, v98, v105, v106
	v_lshlrev_b32_e32 v105, 16, v14
	v_and_b32_e32 v14, 0xffff0000, v14
	v_lshlrev_b32_e32 v106, 16, v15
	v_and_b32_e32 v15, 0xffff0000, v15
	v_add_f32_e32 v107, v105, v14
	v_sub_f32_e32 v14, v105, v14
	v_add_f32_e32 v105, v106, v15
	v_sub_f32_e32 v15, v106, v15
	v_add_f32_e32 v106, v107, v105
	v_sub_f32_e32 v105, v107, v105
	v_add_f32_e32 v108, v14, v15
	v_sub_f32_e32 v14, v14, v15
	v_xor_b32_e32 v15, v82, v106
	v_xor_b32_e32 v107, v82, v105
	s_nop 0
	v_add_f32_dpp v15, v106, v15 quad_perm:[1,0,3,2] row_mask:0xf bank_mask:0xf bound_ctrl:1
	v_xor_b32_e32 v106, v82, v108
	v_add_f32_dpp v105, v105, v107 quad_perm:[1,0,3,2] row_mask:0xf bank_mask:0xf bound_ctrl:1
	v_xor_b32_e32 v107, v82, v14
	v_add_f32_dpp v106, v108, v106 quad_perm:[1,0,3,2] row_mask:0xf bank_mask:0xf bound_ctrl:1
	s_nop 0
	v_add_f32_dpp v14, v14, v107 quad_perm:[1,0,3,2] row_mask:0xf bank_mask:0xf bound_ctrl:1
	v_xor_b32_e32 v200, v83, v15
	v_xor_b32_e32 v201, v83, v106
	v_xor_b32_e32 v202, v83, v105
	v_xor_b32_e32 v203, v83, v14
	v_add_f32_dpp v204, v15, v200 quad_perm:[2,3,0,1] row_mask:0xf bank_mask:0xf bound_ctrl:1
	v_add_f32_dpp v205, v106, v201 quad_perm:[2,3,0,1] row_mask:0xf bank_mask:0xf bound_ctrl:1
	v_add_f32_dpp v206, v105, v202 quad_perm:[2,3,0,1] row_mask:0xf bank_mask:0xf bound_ctrl:1
	v_add_f32_dpp v207, v14, v203 quad_perm:[2,3,0,1] row_mask:0xf bank_mask:0xf bound_ctrl:1
	v_xor_b32_e32 v200, v84, v204
	v_xor_b32_e32 v201, v84, v205
	v_xor_b32_e32 v202, v84, v206
	v_xor_b32_e32 v203, v84, v207
	v_add_f32_dpp v15, v204, v200 row_shl:4 row_mask:0xf bank_mask:0x5
	v_add_f32_dpp v106, v205, v201 row_shl:4 row_mask:0xf bank_mask:0x5
	v_add_f32_dpp v105, v206, v202 row_shl:4 row_mask:0xf bank_mask:0x5
	v_add_f32_dpp v14, v207, v203 row_shl:4 row_mask:0xf bank_mask:0x5
	v_add_f32_dpp v15, v204, v200 row_shr:4 row_mask:0xf bank_mask:0xa
	v_add_f32_dpp v106, v205, v201 row_shr:4 row_mask:0xf bank_mask:0xa
	v_add_f32_dpp v105, v206, v202 row_shr:4 row_mask:0xf bank_mask:0xa
	v_add_f32_dpp v14, v207, v203 row_shr:4 row_mask:0xf bank_mask:0xa
	v_max_f32_e64 v107, |v15|, |v106|
	v_max_f32_e64 v108, |v105|, |v14|
	v_max3_f32 v98, v98, v107, v108
	v_lshlrev_b32_e32 v107, 16, v12
	v_and_b32_e32 v12, 0xffff0000, v12
	v_lshlrev_b32_e32 v108, 16, v13
	v_and_b32_e32 v13, 0xffff0000, v13
	v_add_f32_e32 v109, v107, v12
	v_sub_f32_e32 v12, v107, v12
	v_add_f32_e32 v107, v108, v13
	v_sub_f32_e32 v13, v108, v13
	v_add_f32_e32 v108, v109, v107
	v_sub_f32_e32 v107, v109, v107
	v_add_f32_e32 v110, v12, v13
	v_sub_f32_e32 v12, v12, v13
	v_xor_b32_e32 v13, v82, v108
	v_xor_b32_e32 v109, v82, v107
	s_nop 0
	v_add_f32_dpp v13, v108, v13 quad_perm:[1,0,3,2] row_mask:0xf bank_mask:0xf bound_ctrl:1
	v_xor_b32_e32 v108, v82, v110
	v_add_f32_dpp v107, v107, v109 quad_perm:[1,0,3,2] row_mask:0xf bank_mask:0xf bound_ctrl:1
	v_xor_b32_e32 v109, v82, v12
	v_add_f32_dpp v108, v110, v108 quad_perm:[1,0,3,2] row_mask:0xf bank_mask:0xf bound_ctrl:1
	s_nop 0
	v_add_f32_dpp v12, v12, v109 quad_perm:[1,0,3,2] row_mask:0xf bank_mask:0xf bound_ctrl:1
	v_xor_b32_e32 v200, v83, v13
	v_xor_b32_e32 v201, v83, v108
	v_xor_b32_e32 v202, v83, v107
	v_xor_b32_e32 v203, v83, v12
	v_add_f32_dpp v204, v13, v200 quad_perm:[2,3,0,1] row_mask:0xf bank_mask:0xf bound_ctrl:1
	v_add_f32_dpp v205, v108, v201 quad_perm:[2,3,0,1] row_mask:0xf bank_mask:0xf bound_ctrl:1
	v_add_f32_dpp v206, v107, v202 quad_perm:[2,3,0,1] row_mask:0xf bank_mask:0xf bound_ctrl:1
	v_add_f32_dpp v207, v12, v203 quad_perm:[2,3,0,1] row_mask:0xf bank_mask:0xf bound_ctrl:1
	v_xor_b32_e32 v200, v84, v204
	v_xor_b32_e32 v201, v84, v205
	v_xor_b32_e32 v202, v84, v206
	v_xor_b32_e32 v203, v84, v207
	v_add_f32_dpp v13, v204, v200 row_shl:4 row_mask:0xf bank_mask:0x5
	v_add_f32_dpp v108, v205, v201 row_shl:4 row_mask:0xf bank_mask:0x5
	v_add_f32_dpp v107, v206, v202 row_shl:4 row_mask:0xf bank_mask:0x5
	v_add_f32_dpp v12, v207, v203 row_shl:4 row_mask:0xf bank_mask:0x5
	v_add_f32_dpp v13, v204, v200 row_shr:4 row_mask:0xf bank_mask:0xa
	v_add_f32_dpp v108, v205, v201 row_shr:4 row_mask:0xf bank_mask:0xa
	v_add_f32_dpp v107, v206, v202 row_shr:4 row_mask:0xf bank_mask:0xa
	v_add_f32_dpp v12, v207, v203 row_shr:4 row_mask:0xf bank_mask:0xa
	v_max_f32_e64 v109, |v13|, |v108|
	v_max_f32_e64 v110, |v107|, |v12|
	v_max3_f32 v98, v98, v109, v110
	v_lshlrev_b32_e32 v109, 16, v10
	v_and_b32_e32 v10, 0xffff0000, v10
	v_lshlrev_b32_e32 v110, 16, v11
	v_and_b32_e32 v11, 0xffff0000, v11
	v_add_f32_e32 v111, v109, v10
	v_sub_f32_e32 v10, v109, v10
	v_add_f32_e32 v109, v110, v11
	v_sub_f32_e32 v11, v110, v11
	v_add_f32_e32 v110, v111, v109
	v_sub_f32_e32 v109, v111, v109
	v_add_f32_e32 v112, v10, v11
	v_sub_f32_e32 v10, v10, v11
	v_xor_b32_e32 v11, v82, v110
	v_xor_b32_e32 v111, v82, v109
	s_nop 0
	v_add_f32_dpp v11, v110, v11 quad_perm:[1,0,3,2] row_mask:0xf bank_mask:0xf bound_ctrl:1
	v_xor_b32_e32 v110, v82, v112
	v_add_f32_dpp v109, v109, v111 quad_perm:[1,0,3,2] row_mask:0xf bank_mask:0xf bound_ctrl:1
	v_xor_b32_e32 v111, v82, v10
	v_add_f32_dpp v110, v112, v110 quad_perm:[1,0,3,2] row_mask:0xf bank_mask:0xf bound_ctrl:1
	s_nop 0
	v_add_f32_dpp v10, v10, v111 quad_perm:[1,0,3,2] row_mask:0xf bank_mask:0xf bound_ctrl:1
	v_xor_b32_e32 v200, v83, v11
	v_xor_b32_e32 v201, v83, v110
	v_xor_b32_e32 v202, v83, v109
	v_xor_b32_e32 v203, v83, v10
	v_add_f32_dpp v204, v11, v200 quad_perm:[2,3,0,1] row_mask:0xf bank_mask:0xf bound_ctrl:1
	v_add_f32_dpp v205, v110, v201 quad_perm:[2,3,0,1] row_mask:0xf bank_mask:0xf bound_ctrl:1
	v_add_f32_dpp v206, v109, v202 quad_perm:[2,3,0,1] row_mask:0xf bank_mask:0xf bound_ctrl:1
	v_add_f32_dpp v207, v10, v203 quad_perm:[2,3,0,1] row_mask:0xf bank_mask:0xf bound_ctrl:1
	v_xor_b32_e32 v200, v84, v204
	v_xor_b32_e32 v201, v84, v205
	v_xor_b32_e32 v202, v84, v206
	v_xor_b32_e32 v203, v84, v207
	v_add_f32_dpp v11, v204, v200 row_shl:4 row_mask:0xf bank_mask:0x5
	v_add_f32_dpp v110, v205, v201 row_shl:4 row_mask:0xf bank_mask:0x5
	v_add_f32_dpp v109, v206, v202 row_shl:4 row_mask:0xf bank_mask:0x5
	v_add_f32_dpp v10, v207, v203 row_shl:4 row_mask:0xf bank_mask:0x5
	v_add_f32_dpp v11, v204, v200 row_shr:4 row_mask:0xf bank_mask:0xa
	v_add_f32_dpp v110, v205, v201 row_shr:4 row_mask:0xf bank_mask:0xa
	v_add_f32_dpp v109, v206, v202 row_shr:4 row_mask:0xf bank_mask:0xa
	v_add_f32_dpp v10, v207, v203 row_shr:4 row_mask:0xf bank_mask:0xa
	v_max_f32_e64 v111, |v11|, |v110|
	v_max_f32_e64 v112, |v109|, |v10|
	v_max3_f32 v98, v98, v111, v112
	v_lshlrev_b32_e32 v111, 16, v8
	v_and_b32_e32 v8, 0xffff0000, v8
	v_lshlrev_b32_e32 v112, 16, v9
	v_and_b32_e32 v9, 0xffff0000, v9
	v_add_f32_e32 v113, v111, v8
	v_sub_f32_e32 v8, v111, v8
	v_add_f32_e32 v111, v112, v9
	v_sub_f32_e32 v9, v112, v9
	v_add_f32_e32 v112, v113, v111
	v_sub_f32_e32 v111, v113, v111
	v_add_f32_e32 v114, v8, v9
	v_sub_f32_e32 v8, v8, v9
	v_xor_b32_e32 v9, v82, v112
	v_xor_b32_e32 v113, v82, v111
	s_nop 0
	v_add_f32_dpp v9, v112, v9 quad_perm:[1,0,3,2] row_mask:0xf bank_mask:0xf bound_ctrl:1
	v_xor_b32_e32 v112, v82, v114
	v_add_f32_dpp v111, v111, v113 quad_perm:[1,0,3,2] row_mask:0xf bank_mask:0xf bound_ctrl:1
	v_xor_b32_e32 v113, v82, v8
	v_add_f32_dpp v112, v114, v112 quad_perm:[1,0,3,2] row_mask:0xf bank_mask:0xf bound_ctrl:1
	s_nop 0
	v_add_f32_dpp v8, v8, v113 quad_perm:[1,0,3,2] row_mask:0xf bank_mask:0xf bound_ctrl:1
	v_xor_b32_e32 v200, v83, v9
	v_xor_b32_e32 v201, v83, v112
	v_xor_b32_e32 v202, v83, v111
	v_xor_b32_e32 v203, v83, v8
	v_add_f32_dpp v204, v9, v200 quad_perm:[2,3,0,1] row_mask:0xf bank_mask:0xf bound_ctrl:1
	v_add_f32_dpp v205, v112, v201 quad_perm:[2,3,0,1] row_mask:0xf bank_mask:0xf bound_ctrl:1
	v_add_f32_dpp v206, v111, v202 quad_perm:[2,3,0,1] row_mask:0xf bank_mask:0xf bound_ctrl:1
	v_add_f32_dpp v207, v8, v203 quad_perm:[2,3,0,1] row_mask:0xf bank_mask:0xf bound_ctrl:1
	v_xor_b32_e32 v200, v84, v204
	v_xor_b32_e32 v201, v84, v205
	v_xor_b32_e32 v202, v84, v206
	v_xor_b32_e32 v203, v84, v207
	v_add_f32_dpp v9, v204, v200 row_shl:4 row_mask:0xf bank_mask:0x5
	v_add_f32_dpp v112, v205, v201 row_shl:4 row_mask:0xf bank_mask:0x5
	v_add_f32_dpp v111, v206, v202 row_shl:4 row_mask:0xf bank_mask:0x5
	v_add_f32_dpp v8, v207, v203 row_shl:4 row_mask:0xf bank_mask:0x5
	v_add_f32_dpp v9, v204, v200 row_shr:4 row_mask:0xf bank_mask:0xa
	v_add_f32_dpp v112, v205, v201 row_shr:4 row_mask:0xf bank_mask:0xa
	v_add_f32_dpp v111, v206, v202 row_shr:4 row_mask:0xf bank_mask:0xa
	v_add_f32_dpp v8, v207, v203 row_shr:4 row_mask:0xf bank_mask:0xa
	v_max_f32_e64 v113, |v9|, |v112|
	v_max_f32_e64 v114, |v111|, |v8|
	v_max3_f32 v98, v98, v113, v114
	v_lshlrev_b32_e32 v113, 16, v6
	v_and_b32_e32 v6, 0xffff0000, v6
	v_lshlrev_b32_e32 v114, 16, v7
	v_and_b32_e32 v7, 0xffff0000, v7
	v_add_f32_e32 v115, v113, v6
	v_sub_f32_e32 v6, v113, v6
	v_add_f32_e32 v113, v114, v7
	v_sub_f32_e32 v7, v114, v7
	v_add_f32_e32 v114, v115, v113
	v_sub_f32_e32 v113, v115, v113
	v_add_f32_e32 v116, v6, v7
	v_sub_f32_e32 v6, v6, v7
	v_xor_b32_e32 v7, v82, v114
	v_xor_b32_e32 v115, v82, v113
	s_nop 0
	v_add_f32_dpp v7, v114, v7 quad_perm:[1,0,3,2] row_mask:0xf bank_mask:0xf bound_ctrl:1
	v_xor_b32_e32 v114, v82, v116
	v_add_f32_dpp v113, v113, v115 quad_perm:[1,0,3,2] row_mask:0xf bank_mask:0xf bound_ctrl:1
	v_xor_b32_e32 v115, v82, v6
	v_add_f32_dpp v114, v116, v114 quad_perm:[1,0,3,2] row_mask:0xf bank_mask:0xf bound_ctrl:1
	s_nop 0
	v_add_f32_dpp v6, v6, v115 quad_perm:[1,0,3,2] row_mask:0xf bank_mask:0xf bound_ctrl:1
	v_xor_b32_e32 v200, v83, v7
	v_xor_b32_e32 v201, v83, v114
	v_xor_b32_e32 v202, v83, v113
	v_xor_b32_e32 v203, v83, v6
	v_add_f32_dpp v204, v7, v200 quad_perm:[2,3,0,1] row_mask:0xf bank_mask:0xf bound_ctrl:1
	v_add_f32_dpp v205, v114, v201 quad_perm:[2,3,0,1] row_mask:0xf bank_mask:0xf bound_ctrl:1
	v_add_f32_dpp v206, v113, v202 quad_perm:[2,3,0,1] row_mask:0xf bank_mask:0xf bound_ctrl:1
	v_add_f32_dpp v207, v6, v203 quad_perm:[2,3,0,1] row_mask:0xf bank_mask:0xf bound_ctrl:1
	v_xor_b32_e32 v200, v84, v204
	v_xor_b32_e32 v201, v84, v205
	v_xor_b32_e32 v202, v84, v206
	v_xor_b32_e32 v203, v84, v207
	v_add_f32_dpp v7, v204, v200 row_shl:4 row_mask:0xf bank_mask:0x5
	v_add_f32_dpp v114, v205, v201 row_shl:4 row_mask:0xf bank_mask:0x5
	v_add_f32_dpp v113, v206, v202 row_shl:4 row_mask:0xf bank_mask:0x5
	v_add_f32_dpp v6, v207, v203 row_shl:4 row_mask:0xf bank_mask:0x5
	v_add_f32_dpp v7, v204, v200 row_shr:4 row_mask:0xf bank_mask:0xa
	v_add_f32_dpp v114, v205, v201 row_shr:4 row_mask:0xf bank_mask:0xa
	v_add_f32_dpp v113, v206, v202 row_shr:4 row_mask:0xf bank_mask:0xa
	v_add_f32_dpp v6, v207, v203 row_shr:4 row_mask:0xf bank_mask:0xa
	v_max_f32_e64 v115, |v7|, |v114|
	v_max_f32_e64 v116, |v113|, |v6|
	v_max3_f32 v98, v98, v115, v116
	s_waitcnt vmcnt(0)
	v_lshlrev_b32_e32 v115, 16, v4
	v_and_b32_e32 v4, 0xffff0000, v4
	v_lshlrev_b32_e32 v116, 16, v5
	v_and_b32_e32 v5, 0xffff0000, v5
	v_add_f32_e32 v117, v115, v4
	v_sub_f32_e32 v4, v115, v4
	v_add_f32_e32 v115, v116, v5
	v_sub_f32_e32 v5, v116, v5
	v_add_f32_e32 v116, v117, v115
	v_sub_f32_e32 v115, v117, v115
	v_add_f32_e32 v118, v4, v5
	v_sub_f32_e32 v4, v4, v5
	v_xor_b32_e32 v5, v82, v116
	v_xor_b32_e32 v117, v82, v115
	s_nop 0
	v_add_f32_dpp v5, v116, v5 quad_perm:[1,0,3,2] row_mask:0xf bank_mask:0xf bound_ctrl:1
	v_xor_b32_e32 v116, v82, v118
	v_add_f32_dpp v115, v115, v117 quad_perm:[1,0,3,2] row_mask:0xf bank_mask:0xf bound_ctrl:1
	v_xor_b32_e32 v117, v82, v4
	v_add_f32_dpp v116, v118, v116 quad_perm:[1,0,3,2] row_mask:0xf bank_mask:0xf bound_ctrl:1
	s_nop 0
	v_add_f32_dpp v4, v4, v117 quad_perm:[1,0,3,2] row_mask:0xf bank_mask:0xf bound_ctrl:1
	v_xor_b32_e32 v200, v83, v5
	v_xor_b32_e32 v201, v83, v116
	v_xor_b32_e32 v202, v83, v115
	v_xor_b32_e32 v203, v83, v4
	v_add_f32_dpp v204, v5, v200 quad_perm:[2,3,0,1] row_mask:0xf bank_mask:0xf bound_ctrl:1
	v_add_f32_dpp v205, v116, v201 quad_perm:[2,3,0,1] row_mask:0xf bank_mask:0xf bound_ctrl:1
	v_add_f32_dpp v206, v115, v202 quad_perm:[2,3,0,1] row_mask:0xf bank_mask:0xf bound_ctrl:1
	v_add_f32_dpp v207, v4, v203 quad_perm:[2,3,0,1] row_mask:0xf bank_mask:0xf bound_ctrl:1
	v_xor_b32_e32 v200, v84, v204
	v_xor_b32_e32 v201, v84, v205
	v_xor_b32_e32 v202, v84, v206
	v_xor_b32_e32 v203, v84, v207
	v_add_f32_dpp v5, v204, v200 row_shl:4 row_mask:0xf bank_mask:0x5
	v_add_f32_dpp v116, v205, v201 row_shl:4 row_mask:0xf bank_mask:0x5
	v_add_f32_dpp v115, v206, v202 row_shl:4 row_mask:0xf bank_mask:0x5
	v_add_f32_dpp v4, v207, v203 row_shl:4 row_mask:0xf bank_mask:0x5
	v_add_f32_dpp v5, v204, v200 row_shr:4 row_mask:0xf bank_mask:0xa
	v_add_f32_dpp v116, v205, v201 row_shr:4 row_mask:0xf bank_mask:0xa
	v_add_f32_dpp v115, v206, v202 row_shr:4 row_mask:0xf bank_mask:0xa
	v_add_f32_dpp v4, v207, v203 row_shr:4 row_mask:0xf bank_mask:0xa
	v_max_f32_e64 v117, |v5|, |v116|
	v_max_f32_e64 v118, |v115|, |v4|
	v_max3_f32 v98, v98, v117, v118
	ds_swizzle_b32 v117, v98 offset:swizzle(SWAP,1)
	s_waitcnt lgkmcnt(0)
	v_max_f32_e32 v94, v117, v117
	v_max_f32_e32 v94, v98, v94
	ds_swizzle_b32 v95, v94 offset:swizzle(SWAP,2)
	v_cvt_pk_bf16_f32 v98, v101, v18
	s_waitcnt lgkmcnt(0)
	v_max_f32_e32 v18, v95, v95
	v_max_f32_e32 v18, v94, v18
	ds_swizzle_b32 v20, v18 offset:swizzle(SWAP,4)
	v_cvt_pk_bf16_f32 v94, v17, v104
	v_cvt_pk_bf16_f32 v95, v103, v16
	v_cvt_pk_bf16_f32 v99, v15, v106
	v_cvt_pk_bf16_f32 v100, v105, v14
	s_waitcnt lgkmcnt(0)
	v_max_f32_e32 v14, v20, v20
	v_max_f32_e32 v14, v18, v14
	ds_swizzle_b32 v16, v14 offset:swizzle(SWAP,8)
	v_cvt_pk_bf16_f32 v18, v13, v108
	v_cvt_pk_bf16_f32 v101, v107, v12
	v_cvt_pk_bf16_f32 v15, v11, v110
	v_cvt_pk_bf16_f32 v17, v109, v10
	s_waitcnt lgkmcnt(0)
	v_max_f32_e32 v10, v16, v16
	v_max_f32_e32 v10, v14, v10
	ds_swizzle_b32 v12, v10 offset:swizzle(SWAP,16)
	v_cvt_pk_bf16_f32 v13, v9, v112
	v_cvt_pk_bf16_f32 v14, v111, v8
	v_cvt_pk_bf16_f32 v9, v7, v114
	v_cvt_pk_bf16_f32 v11, v113, v6
	s_waitcnt lgkmcnt(0)
	v_max_f32_e32 v6, v12, v12
	v_max_f32_e32 v6, v10, v6
	v_mov_b32_e32 v7, v6
	s_nop 1
	v_permlane32_swap_b32_e32 v6, v7
	v_max_f32_e32 v7, v7, v7
	v_max_f32_e32 v6, v6, v6
	v_max_f32_e32 v6, v6, v7
	v_mul_f32_e32 v8, 0x3f808000, v6
	v_div_scale_f32 v6, s[18:19], v8, v8, s27
	v_rcp_f32_e32 v7, v6
	v_cvt_pk_bf16_f32 v10, v5, v116
	v_cvt_pk_bf16_f32 v12, v115, v4
	v_lshl_add_u64 v[4:5], s[8:9], 0, v[0:1]
	v_fma_f32 v16, -v6, v7, 1.0
	v_fmac_f32_e32 v7, v16, v7
	v_div_scale_f32 v16, vcc, s27, v8, s27
	v_mul_f32_e32 v20, v16, v7
	v_fma_f32 v21, -v6, v20, v16
	v_fmac_f32_e32 v20, v21, v7
	v_fma_f32 v6, -v6, v20, v16
	v_div_fmas_f32 v6, v6, v7, v20
	v_div_fixup_f32 v6, v6, v8, s27
	v_cmp_lt_f32_e32 vcc, 0, v8
	v_lshlrev_b32_e32 v7, 16, v87
	v_lshlrev_b32_e32 v20, 16, v86
	v_cndmask_b32_e32 v16, 0, v6, vcc
	v_and_b32_e32 v6, 0xffff0000, v87
	v_fmaak_f32 v6, v6, v16, 0x4b400000
	v_fmaak_f32 v7, v7, v16, 0x4b400000
	v_perm_b32 v6, v6, v7, s28
	v_and_b32_e32 v7, 0xffff0000, v86
	v_fmaak_f32 v7, v7, v16, 0x4b400000
	v_fmaak_f32 v20, v20, v16, 0x4b400000
	v_perm_b32 v7, v7, v20, s28
	v_add_co_u32_e32 v20, vcc, s30, v4
	v_perm_b32 v86, v6, v7, s29
	s_nop 0
	v_addc_co_u32_e32 v21, vcc, 0, v5, vcc
	v_add_co_u32_e32 v6, vcc, s31, v4
	v_lshlrev_b32_e32 v87, 16, v89
	s_nop 0
	v_addc_co_u32_e32 v7, vcc, 0, v5, vcc
	global_store_dword v[6:7], v86, off offset:-4096
	v_and_b32_e32 v86, 0xffff0000, v89
	v_fmaak_f32 v86, v86, v16, 0x4b400000
	v_fmaak_f32 v87, v87, v16, 0x4b400000
	v_perm_b32 v86, v86, v87, s28
	v_and_b32_e32 v87, 0xffff0000, v88
	v_lshlrev_b32_e32 v88, 16, v88
	v_fmaak_f32 v87, v87, v16, 0x4b400000
	v_fmaak_f32 v88, v88, v16, 0x4b400000
	v_perm_b32 v87, v87, v88, s28
	v_perm_b32 v86, v86, v87, s29
	global_store_dword v[20:21], v86, off offset:256
	v_and_b32_e32 v86, 0xffff0000, v91
	v_lshlrev_b32_e32 v87, 16, v91
	v_fmaak_f32 v86, v86, v16, 0x4b400000
	v_fmaak_f32 v87, v87, v16, 0x4b400000
	v_perm_b32 v86, v86, v87, s28
	v_and_b32_e32 v87, 0xffff0000, v90
	v_lshlrev_b32_e32 v88, 16, v90
	v_fmaak_f32 v87, v87, v16, 0x4b400000
	v_fmaak_f32 v88, v88, v16, 0x4b400000
	v_perm_b32 v87, v87, v88, s28
	v_perm_b32 v86, v86, v87, s29
	global_store_dword v[20:21], v86, off offset:512
	v_and_b32_e32 v86, 0xffff0000, v93
	v_lshlrev_b32_e32 v87, 16, v93
	v_fmaak_f32 v86, v86, v16, 0x4b400000
	v_fmaak_f32 v87, v87, v16, 0x4b400000
	v_perm_b32 v86, v86, v87, s28
	v_and_b32_e32 v87, 0xffff0000, v92
	v_lshlrev_b32_e32 v88, 16, v92
	v_fmaak_f32 v87, v87, v16, 0x4b400000
	v_fmaak_f32 v88, v88, v16, 0x4b400000
	v_perm_b32 v87, v87, v88, s28
	v_perm_b32 v86, v86, v87, s29
	global_store_dword v[20:21], v86, off offset:768
	v_and_b32_e32 v86, 0xffff0000, v81
	v_lshlrev_b32_e32 v81, 16, v81
	v_fmaak_f32 v86, v86, v16, 0x4b400000
	v_fmaak_f32 v81, v81, v16, 0x4b400000
	v_perm_b32 v81, v86, v81, s28
	v_and_b32_e32 v86, 0xffff0000, v80
	v_lshlrev_b32_e32 v80, 16, v80
	v_fmaak_f32 v86, v86, v16, 0x4b400000
	v_fmaak_f32 v80, v80, v16, 0x4b400000
	v_perm_b32 v80, v86, v80, s28
	v_perm_b32 v80, v81, v80, s29
	global_store_dword v[20:21], v80, off offset:1024
	v_and_b32_e32 v80, 0xffff0000, v79
	v_lshlrev_b32_e32 v79, 16, v79
	v_fmaak_f32 v80, v80, v16, 0x4b400000
	v_fmaak_f32 v79, v79, v16, 0x4b400000
	v_perm_b32 v79, v80, v79, s28
	v_and_b32_e32 v80, 0xffff0000, v78
	v_lshlrev_b32_e32 v78, 16, v78
	v_fmaak_f32 v80, v80, v16, 0x4b400000
	v_fmaak_f32 v78, v78, v16, 0x4b400000
	v_perm_b32 v78, v80, v78, s28
	v_perm_b32 v78, v79, v78, s29
	global_store_dword v[20:21], v78, off offset:1280
	v_and_b32_e32 v78, 0xffff0000, v77
	v_lshlrev_b32_e32 v77, 16, v77
	v_fmaak_f32 v78, v78, v16, 0x4b400000
	v_fmaak_f32 v77, v77, v16, 0x4b400000
	v_perm_b32 v77, v78, v77, s28
	v_and_b32_e32 v78, 0xffff0000, v76
	v_lshlrev_b32_e32 v76, 16, v76
	v_fmaak_f32 v78, v78, v16, 0x4b400000
	v_fmaak_f32 v76, v76, v16, 0x4b400000
	v_perm_b32 v76, v78, v76, s28
	v_perm_b32 v76, v77, v76, s29
	global_store_dword v[20:21], v76, off offset:1536
	v_and_b32_e32 v76, 0xffff0000, v75
	v_lshlrev_b32_e32 v75, 16, v75
	v_fmaak_f32 v76, v76, v16, 0x4b400000
	v_fmaak_f32 v75, v75, v16, 0x4b400000
	v_perm_b32 v75, v76, v75, s28
	v_and_b32_e32 v76, 0xffff0000, v74
	v_lshlrev_b32_e32 v74, 16, v74
	v_fmaak_f32 v76, v76, v16, 0x4b400000
	v_fmaak_f32 v74, v74, v16, 0x4b400000
	v_perm_b32 v74, v76, v74, s28
	v_perm_b32 v74, v75, v74, s29
	global_store_dword v[20:21], v74, off offset:1792
	v_and_b32_e32 v74, 0xffff0000, v73
	v_lshlrev_b32_e32 v73, 16, v73
	v_fmaak_f32 v74, v74, v16, 0x4b400000
	v_fmaak_f32 v73, v73, v16, 0x4b400000
	v_perm_b32 v73, v74, v73, s28
	v_and_b32_e32 v74, 0xffff0000, v72
	v_lshlrev_b32_e32 v72, 16, v72
	v_fmaak_f32 v74, v74, v16, 0x4b400000
	v_fmaak_f32 v72, v72, v16, 0x4b400000
	v_perm_b32 v72, v74, v72, s28
	v_perm_b32 v72, v73, v72, s29
	global_store_dword v[20:21], v72, off offset:2048
	v_and_b32_e32 v72, 0xffff0000, v71
	v_lshlrev_b32_e32 v71, 16, v71
	v_fmaak_f32 v72, v72, v16, 0x4b400000
	v_fmaak_f32 v71, v71, v16, 0x4b400000
	v_perm_b32 v71, v72, v71, s28
	v_and_b32_e32 v72, 0xffff0000, v70
	v_lshlrev_b32_e32 v70, 16, v70
	v_fmaak_f32 v72, v72, v16, 0x4b400000
	v_fmaak_f32 v70, v70, v16, 0x4b400000
	v_perm_b32 v70, v72, v70, s28
	v_perm_b32 v70, v71, v70, s29
	global_store_dword v[20:21], v70, off offset:2304
	v_and_b32_e32 v70, 0xffff0000, v69
	v_lshlrev_b32_e32 v69, 16, v69
	v_fmaak_f32 v70, v70, v16, 0x4b400000
	v_fmaak_f32 v69, v69, v16, 0x4b400000
	v_perm_b32 v69, v70, v69, s28
	v_and_b32_e32 v70, 0xffff0000, v68
	v_lshlrev_b32_e32 v68, 16, v68
	v_fmaak_f32 v70, v70, v16, 0x4b400000
	v_fmaak_f32 v68, v68, v16, 0x4b400000
	v_perm_b32 v68, v70, v68, s28
	v_perm_b32 v68, v69, v68, s29
	global_store_dword v[20:21], v68, off offset:2560
	v_and_b32_e32 v68, 0xffff0000, v67
	v_lshlrev_b32_e32 v67, 16, v67
	v_fmaak_f32 v68, v68, v16, 0x4b400000
	v_fmaak_f32 v67, v67, v16, 0x4b400000
	v_perm_b32 v67, v68, v67, s28
	v_and_b32_e32 v68, 0xffff0000, v66
	v_lshlrev_b32_e32 v66, 16, v66
	v_fmaak_f32 v68, v68, v16, 0x4b400000
	v_fmaak_f32 v66, v66, v16, 0x4b400000
	v_perm_b32 v66, v68, v66, s28
	v_perm_b32 v66, v67, v66, s29
	global_store_dword v[20:21], v66, off offset:2816
	v_and_b32_e32 v66, 0xffff0000, v65
	v_lshlrev_b32_e32 v65, 16, v65
	v_fmaak_f32 v66, v66, v16, 0x4b400000
	v_fmaak_f32 v65, v65, v16, 0x4b400000
	v_perm_b32 v65, v66, v65, s28
	v_and_b32_e32 v66, 0xffff0000, v64
	v_lshlrev_b32_e32 v64, 16, v64
	v_fmaak_f32 v66, v66, v16, 0x4b400000
	v_fmaak_f32 v64, v64, v16, 0x4b400000
	v_perm_b32 v64, v66, v64, s28
	v_perm_b32 v64, v65, v64, s29
	global_store_dword v[20:21], v64, off offset:3072
	v_and_b32_e32 v64, 0xffff0000, v63
	v_lshlrev_b32_e32 v63, 16, v63
	v_fmaak_f32 v64, v64, v16, 0x4b400000
	v_fmaak_f32 v63, v63, v16, 0x4b400000
	v_perm_b32 v63, v64, v63, s28
	v_and_b32_e32 v64, 0xffff0000, v62
	v_lshlrev_b32_e32 v62, 16, v62
	v_fmaak_f32 v64, v64, v16, 0x4b400000
	v_fmaak_f32 v62, v62, v16, 0x4b400000
	v_perm_b32 v62, v64, v62, s28
	v_perm_b32 v62, v63, v62, s29
	global_store_dword v[20:21], v62, off offset:3328
	v_and_b32_e32 v62, 0xffff0000, v61
	v_lshlrev_b32_e32 v61, 16, v61
	v_fmaak_f32 v62, v62, v16, 0x4b400000
	v_fmaak_f32 v61, v61, v16, 0x4b400000
	v_perm_b32 v61, v62, v61, s28
	v_and_b32_e32 v62, 0xffff0000, v60
	v_lshlrev_b32_e32 v60, 16, v60
	v_fmaak_f32 v62, v62, v16, 0x4b400000
	v_fmaak_f32 v60, v60, v16, 0x4b400000
	v_perm_b32 v60, v62, v60, s28
	v_perm_b32 v60, v61, v60, s29
	global_store_dword v[20:21], v60, off offset:3584
	v_and_b32_e32 v60, 0xffff0000, v59
	v_lshlrev_b32_e32 v59, 16, v59
	v_fmaak_f32 v60, v60, v16, 0x4b400000
	v_fmaak_f32 v59, v59, v16, 0x4b400000
	v_perm_b32 v59, v60, v59, s28
	v_and_b32_e32 v60, 0xffff0000, v58
	v_lshlrev_b32_e32 v58, 16, v58
	v_fmaak_f32 v60, v60, v16, 0x4b400000
	v_fmaak_f32 v58, v58, v16, 0x4b400000
	v_perm_b32 v58, v60, v58, s28
	v_perm_b32 v58, v59, v58, s29
	global_store_dword v[20:21], v58, off offset:3840
	v_and_b32_e32 v20, 0xffff0000, v57
	v_lshlrev_b32_e32 v21, 16, v57
	v_fmaak_f32 v20, v20, v16, 0x4b400000
	v_fmaak_f32 v21, v21, v16, 0x4b400000
	v_perm_b32 v20, v20, v21, s28
	v_and_b32_e32 v21, 0xffff0000, v56
	v_lshlrev_b32_e32 v56, 16, v56
	v_fmaak_f32 v21, v21, v16, 0x4b400000
	v_fmaak_f32 v56, v56, v16, 0x4b400000
	v_perm_b32 v21, v21, v56, s28
	v_perm_b32 v20, v20, v21, s29
	global_store_dword v[6:7], v20, off
	v_and_b32_e32 v20, 0xffff0000, v55
	v_lshlrev_b32_e32 v21, 16, v55
	v_fmaak_f32 v20, v20, v16, 0x4b400000
	v_fmaak_f32 v21, v21, v16, 0x4b400000
	v_perm_b32 v20, v20, v21, s28
	v_and_b32_e32 v21, 0xffff0000, v54
	v_lshlrev_b32_e32 v54, 16, v54
	v_fmaak_f32 v21, v21, v16, 0x4b400000
	v_fmaak_f32 v54, v54, v16, 0x4b400000
	v_perm_b32 v21, v21, v54, s28
	v_perm_b32 v20, v20, v21, s29
	global_store_dword v[6:7], v20, off offset:256
	v_and_b32_e32 v20, 0xffff0000, v53
	v_lshlrev_b32_e32 v21, 16, v53
	v_fmaak_f32 v20, v20, v16, 0x4b400000
	v_fmaak_f32 v21, v21, v16, 0x4b400000
	v_perm_b32 v20, v20, v21, s28
	v_and_b32_e32 v21, 0xffff0000, v52
	v_lshlrev_b32_e32 v52, 16, v52
	v_fmaak_f32 v21, v21, v16, 0x4b400000
	v_fmaak_f32 v52, v52, v16, 0x4b400000
	v_perm_b32 v21, v21, v52, s28
	v_perm_b32 v20, v20, v21, s29
	global_store_dword v[6:7], v20, off offset:512
	v_and_b32_e32 v20, 0xffff0000, v51
	v_lshlrev_b32_e32 v21, 16, v51
	v_fmaak_f32 v20, v20, v16, 0x4b400000
	v_fmaak_f32 v21, v21, v16, 0x4b400000
	v_perm_b32 v20, v20, v21, s28
	v_and_b32_e32 v21, 0xffff0000, v50
	v_lshlrev_b32_e32 v50, 16, v50
	v_fmaak_f32 v21, v21, v16, 0x4b400000
	v_fmaak_f32 v50, v50, v16, 0x4b400000
	v_perm_b32 v21, v21, v50, s28
	v_perm_b32 v20, v20, v21, s29
	global_store_dword v[6:7], v20, off offset:768
	v_and_b32_e32 v20, 0xffff0000, v49
	v_lshlrev_b32_e32 v21, 16, v49
	v_fmaak_f32 v20, v20, v16, 0x4b400000
	v_fmaak_f32 v21, v21, v16, 0x4b400000
	v_perm_b32 v20, v20, v21, s28
	v_and_b32_e32 v21, 0xffff0000, v48
	v_lshlrev_b32_e32 v48, 16, v48
	v_fmaak_f32 v21, v21, v16, 0x4b400000
	v_fmaak_f32 v48, v48, v16, 0x4b400000
	v_perm_b32 v21, v21, v48, s28
	v_perm_b32 v20, v20, v21, s29
	global_store_dword v[6:7], v20, off offset:1024
	v_and_b32_e32 v20, 0xffff0000, v47
	v_lshlrev_b32_e32 v21, 16, v47
	v_fmaak_f32 v20, v20, v16, 0x4b400000
	v_fmaak_f32 v21, v21, v16, 0x4b400000
	v_perm_b32 v20, v20, v21, s28
	v_and_b32_e32 v21, 0xffff0000, v46
	v_lshlrev_b32_e32 v46, 16, v46
	v_fmaak_f32 v21, v21, v16, 0x4b400000
	v_fmaak_f32 v46, v46, v16, 0x4b400000
	v_perm_b32 v21, v21, v46, s28
	v_perm_b32 v20, v20, v21, s29
	global_store_dword v[6:7], v20, off offset:1280
	v_and_b32_e32 v20, 0xffff0000, v45
	v_lshlrev_b32_e32 v21, 16, v45
	v_fmaak_f32 v20, v20, v16, 0x4b400000
	v_fmaak_f32 v21, v21, v16, 0x4b400000
	v_perm_b32 v20, v20, v21, s28
	v_and_b32_e32 v21, 0xffff0000, v44
	v_lshlrev_b32_e32 v44, 16, v44
	v_fmaak_f32 v21, v21, v16, 0x4b400000
	v_fmaak_f32 v44, v44, v16, 0x4b400000
	v_perm_b32 v21, v21, v44, s28
	v_perm_b32 v20, v20, v21, s29
	global_store_dword v[6:7], v20, off offset:1536
	v_and_b32_e32 v20, 0xffff0000, v43
	v_lshlrev_b32_e32 v21, 16, v43
	v_fmaak_f32 v20, v20, v16, 0x4b400000
	v_fmaak_f32 v21, v21, v16, 0x4b400000
	v_perm_b32 v20, v20, v21, s28
	v_and_b32_e32 v21, 0xffff0000, v42
	v_lshlrev_b32_e32 v42, 16, v42
	v_fmaak_f32 v21, v21, v16, 0x4b400000
	v_fmaak_f32 v42, v42, v16, 0x4b400000
	v_perm_b32 v21, v21, v42, s28
	v_perm_b32 v20, v20, v21, s29
	global_store_dword v[6:7], v20, off offset:1792
	v_and_b32_e32 v20, 0xffff0000, v41
	v_lshlrev_b32_e32 v21, 16, v41
	v_fmaak_f32 v20, v20, v16, 0x4b400000
	v_fmaak_f32 v21, v21, v16, 0x4b400000
	v_perm_b32 v20, v20, v21, s28
	v_and_b32_e32 v21, 0xffff0000, v40
	v_lshlrev_b32_e32 v40, 16, v40
	v_fmaak_f32 v21, v21, v16, 0x4b400000
	v_fmaak_f32 v40, v40, v16, 0x4b400000
	v_perm_b32 v21, v21, v40, s28
	v_perm_b32 v20, v20, v21, s29
	global_store_dword v[6:7], v20, off offset:2048
	v_and_b32_e32 v20, 0xffff0000, v39
	v_lshlrev_b32_e32 v21, 16, v39
	v_fmaak_f32 v20, v20, v16, 0x4b400000
	v_fmaak_f32 v21, v21, v16, 0x4b400000
	v_perm_b32 v20, v20, v21, s28
	v_and_b32_e32 v21, 0xffff0000, v38
	v_lshlrev_b32_e32 v38, 16, v38
	v_fmaak_f32 v21, v21, v16, 0x4b400000
	v_fmaak_f32 v38, v38, v16, 0x4b400000
	v_perm_b32 v21, v21, v38, s28
	v_perm_b32 v20, v20, v21, s29
	global_store_dword v[6:7], v20, off offset:2304
	v_and_b32_e32 v20, 0xffff0000, v37
	v_lshlrev_b32_e32 v21, 16, v37
	v_fmaak_f32 v20, v20, v16, 0x4b400000
	v_fmaak_f32 v21, v21, v16, 0x4b400000
	v_perm_b32 v20, v20, v21, s28
	v_and_b32_e32 v21, 0xffff0000, v36
	v_lshlrev_b32_e32 v36, 16, v36
	v_fmaak_f32 v21, v21, v16, 0x4b400000
	v_fmaak_f32 v36, v36, v16, 0x4b400000
	v_perm_b32 v21, v21, v36, s28
	v_perm_b32 v20, v20, v21, s29
	global_store_dword v[6:7], v20, off offset:2560
	v_and_b32_e32 v20, 0xffff0000, v35
	v_lshlrev_b32_e32 v21, 16, v35
	v_fmaak_f32 v20, v20, v16, 0x4b400000
	v_fmaak_f32 v21, v21, v16, 0x4b400000
	v_perm_b32 v20, v20, v21, s28
	v_and_b32_e32 v21, 0xffff0000, v34
	v_lshlrev_b32_e32 v34, 16, v34
	v_fmaak_f32 v21, v21, v16, 0x4b400000
	v_fmaak_f32 v34, v34, v16, 0x4b400000
	v_perm_b32 v21, v21, v34, s28
	v_perm_b32 v20, v20, v21, s29
	global_store_dword v[6:7], v20, off offset:2816
	v_and_b32_e32 v20, 0xffff0000, v33
	v_lshlrev_b32_e32 v21, 16, v33
	v_fmaak_f32 v20, v20, v16, 0x4b400000
	v_fmaak_f32 v21, v21, v16, 0x4b400000
	v_perm_b32 v20, v20, v21, s28
	v_and_b32_e32 v21, 0xffff0000, v32
	v_lshlrev_b32_e32 v32, 16, v32
	v_fmaak_f32 v21, v21, v16, 0x4b400000
	v_fmaak_f32 v32, v32, v16, 0x4b400000
	v_perm_b32 v21, v21, v32, s28
	v_perm_b32 v20, v20, v21, s29
	global_store_dword v[6:7], v20, off offset:3072
	v_and_b32_e32 v20, 0xffff0000, v31
	v_lshlrev_b32_e32 v21, 16, v31
	v_fmaak_f32 v20, v20, v16, 0x4b400000
	v_fmaak_f32 v21, v21, v16, 0x4b400000
	v_perm_b32 v20, v20, v21, s28
	v_and_b32_e32 v21, 0xffff0000, v30
	v_lshlrev_b32_e32 v30, 16, v30
	v_fmaak_f32 v21, v21, v16, 0x4b400000
	v_fmaak_f32 v30, v30, v16, 0x4b400000
	v_perm_b32 v21, v21, v30, s28
	v_perm_b32 v20, v20, v21, s29
	global_store_dword v[6:7], v20, off offset:3328
	v_and_b32_e32 v20, 0xffff0000, v29
	v_lshlrev_b32_e32 v21, 16, v29
	v_fmaak_f32 v20, v20, v16, 0x4b400000
	v_fmaak_f32 v21, v21, v16, 0x4b400000
	v_perm_b32 v20, v20, v21, s28
	v_and_b32_e32 v21, 0xffff0000, v28
	v_lshlrev_b32_e32 v28, 16, v28
	v_fmaak_f32 v21, v21, v16, 0x4b400000
	v_fmaak_f32 v28, v28, v16, 0x4b400000
	v_perm_b32 v21, v21, v28, s28
	v_perm_b32 v20, v20, v21, s29
	global_store_dword v[6:7], v20, off offset:3584
	v_and_b32_e32 v20, 0xffff0000, v27
	v_lshlrev_b32_e32 v21, 16, v27
	v_fmaak_f32 v20, v20, v16, 0x4b400000
	v_fmaak_f32 v21, v21, v16, 0x4b400000
	v_perm_b32 v20, v20, v21, s28
	v_and_b32_e32 v21, 0xffff0000, v26
	v_lshlrev_b32_e32 v26, 16, v26
	v_fmaak_f32 v21, v21, v16, 0x4b400000
	v_fmaak_f32 v26, v26, v16, 0x4b400000
	v_perm_b32 v21, v21, v26, s28
	v_perm_b32 v20, v20, v21, s29
	global_store_dword v[6:7], v20, off offset:3840
	v_and_b32_e32 v6, 0xffff0000, v25
	v_lshlrev_b32_e32 v7, 16, v25
	v_fmaak_f32 v6, v6, v16, 0x4b400000
	v_fmaak_f32 v7, v7, v16, 0x4b400000
	v_perm_b32 v6, v6, v7, s28
	v_and_b32_e32 v7, 0xffff0000, v24
	v_lshlrev_b32_e32 v20, 16, v24
	v_fmaak_f32 v7, v7, v16, 0x4b400000
	v_fmaak_f32 v20, v20, v16, 0x4b400000
	v_perm_b32 v7, v7, v20, s28
	v_add_co_u32_e32 v4, vcc, s34, v4
	v_perm_b32 v6, v6, v7, s29
	s_nop 0
	v_addc_co_u32_e32 v5, vcc, 0, v5, vcc
	global_store_dword v[4:5], v6, off
	v_and_b32_e32 v6, 0xffff0000, v23
	v_lshlrev_b32_e32 v7, 16, v23
	v_fmaak_f32 v6, v6, v16, 0x4b400000
	v_fmaak_f32 v7, v7, v16, 0x4b400000
	v_perm_b32 v6, v6, v7, s28
	v_and_b32_e32 v7, 0xffff0000, v22
	v_lshlrev_b32_e32 v20, 16, v22
	v_fmaak_f32 v7, v7, v16, 0x4b400000
	v_fmaak_f32 v20, v20, v16, 0x4b400000
	v_perm_b32 v7, v7, v20, s28
	v_perm_b32 v6, v6, v7, s29
	global_store_dword v[4:5], v6, off offset:256
	v_and_b32_e32 v6, 0xffff0000, v97
	v_lshlrev_b32_e32 v7, 16, v97
	v_fmaak_f32 v6, v6, v16, 0x4b400000
	v_fmaak_f32 v7, v7, v16, 0x4b400000
	v_perm_b32 v6, v6, v7, s28
	v_and_b32_e32 v7, 0xffff0000, v96
	v_lshlrev_b32_e32 v20, 16, v96
	v_fmaak_f32 v7, v7, v16, 0x4b400000
	v_fmaak_f32 v20, v20, v16, 0x4b400000
	v_perm_b32 v7, v7, v20, s28
	v_perm_b32 v6, v6, v7, s29
	global_store_dword v[4:5], v6, off offset:512
	v_and_b32_e32 v6, 0xffff0000, v98
	v_lshlrev_b32_e32 v7, 16, v98
	v_fmaak_f32 v6, v6, v16, 0x4b400000
	v_fmaak_f32 v7, v7, v16, 0x4b400000
	v_perm_b32 v6, v6, v7, s28
	v_and_b32_e32 v7, 0xffff0000, v19
	v_lshlrev_b32_e32 v19, 16, v19
	v_fmaak_f32 v7, v7, v16, 0x4b400000
	v_fmaak_f32 v19, v19, v16, 0x4b400000
	v_perm_b32 v7, v7, v19, s28
	v_perm_b32 v6, v6, v7, s29
	global_store_dword v[4:5], v6, off offset:768
	v_and_b32_e32 v6, 0xffff0000, v95
	v_lshlrev_b32_e32 v7, 16, v95
	v_fmaak_f32 v6, v6, v16, 0x4b400000
	v_fmaak_f32 v7, v7, v16, 0x4b400000
	v_perm_b32 v6, v6, v7, s28
	v_and_b32_e32 v7, 0xffff0000, v94
	v_lshlrev_b32_e32 v19, 16, v94
	v_fmaak_f32 v7, v7, v16, 0x4b400000
	v_fmaak_f32 v19, v19, v16, 0x4b400000
	v_perm_b32 v7, v7, v19, s28
	v_perm_b32 v6, v6, v7, s29
	global_store_dword v[4:5], v6, off offset:1024
	v_and_b32_e32 v6, 0xffff0000, v100
	v_lshlrev_b32_e32 v7, 16, v100
	v_fmaak_f32 v6, v6, v16, 0x4b400000
	v_fmaak_f32 v7, v7, v16, 0x4b400000
	v_perm_b32 v6, v6, v7, s28
	v_and_b32_e32 v7, 0xffff0000, v99
	v_lshlrev_b32_e32 v19, 16, v99
	v_fmaak_f32 v7, v7, v16, 0x4b400000
	v_fmaak_f32 v19, v19, v16, 0x4b400000
	v_perm_b32 v7, v7, v19, s28
	v_perm_b32 v6, v6, v7, s29
	global_store_dword v[4:5], v6, off offset:1280
	v_and_b32_e32 v6, 0xffff0000, v101
	v_lshlrev_b32_e32 v7, 16, v101
	v_fmaak_f32 v6, v6, v16, 0x4b400000
	v_fmaak_f32 v7, v7, v16, 0x4b400000
	v_perm_b32 v6, v6, v7, s28
	v_and_b32_e32 v7, 0xffff0000, v18
	v_lshlrev_b32_e32 v18, 16, v18
	v_fmaak_f32 v7, v7, v16, 0x4b400000
	v_fmaak_f32 v18, v18, v16, 0x4b400000
	v_perm_b32 v7, v7, v18, s28
	v_perm_b32 v6, v6, v7, s29
	global_store_dword v[4:5], v6, off offset:1536
	v_and_b32_e32 v6, 0xffff0000, v17
	v_lshlrev_b32_e32 v7, 16, v17
	v_fmaak_f32 v6, v6, v16, 0x4b400000
	v_fmaak_f32 v7, v7, v16, 0x4b400000
	v_perm_b32 v6, v6, v7, s28
	v_and_b32_e32 v7, 0xffff0000, v15
	v_lshlrev_b32_e32 v15, 16, v15
	v_fmaak_f32 v7, v7, v16, 0x4b400000
	v_fmaak_f32 v15, v15, v16, 0x4b400000
	v_perm_b32 v7, v7, v15, s28
	v_perm_b32 v6, v6, v7, s29
	global_store_dword v[4:5], v6, off offset:1792
	v_and_b32_e32 v6, 0xffff0000, v14
	v_lshlrev_b32_e32 v7, 16, v14
	v_fmaak_f32 v6, v6, v16, 0x4b400000
	v_fmaak_f32 v7, v7, v16, 0x4b400000
	v_perm_b32 v6, v6, v7, s28
	v_and_b32_e32 v7, 0xffff0000, v13
	v_lshlrev_b32_e32 v13, 16, v13
	v_fmaak_f32 v7, v7, v16, 0x4b400000
	v_fmaak_f32 v13, v13, v16, 0x4b400000
	v_perm_b32 v7, v7, v13, s28
	v_perm_b32 v6, v6, v7, s29
	global_store_dword v[4:5], v6, off offset:2048
	v_and_b32_e32 v6, 0xffff0000, v11
	v_lshlrev_b32_e32 v7, 16, v11
	v_fmaak_f32 v6, v6, v16, 0x4b400000
	v_fmaak_f32 v7, v7, v16, 0x4b400000
	v_perm_b32 v6, v6, v7, s28
	v_and_b32_e32 v7, 0xffff0000, v9
	v_lshlrev_b32_e32 v9, 16, v9
	v_fmaak_f32 v7, v7, v16, 0x4b400000
	v_fmaak_f32 v9, v9, v16, 0x4b400000
	v_perm_b32 v7, v7, v9, s28
	v_perm_b32 v6, v6, v7, s29
	global_store_dword v[4:5], v6, off offset:2304
	v_and_b32_e32 v6, 0xffff0000, v12
	v_lshlrev_b32_e32 v7, 16, v12
	v_fmaak_f32 v6, v6, v16, 0x4b400000
	v_fmaak_f32 v7, v7, v16, 0x4b400000
	v_perm_b32 v6, v6, v7, s28
	v_and_b32_e32 v7, 0xffff0000, v10
	v_lshlrev_b32_e32 v9, 16, v10
	v_fmaak_f32 v7, v7, v16, 0x4b400000
	v_fmaak_f32 v9, v9, v16, 0x4b400000
	v_perm_b32 v7, v7, v9, s28
	v_perm_b32 v6, v6, v7, s29
	global_store_dword v[4:5], v6, off offset:2560
	s_and_saveexec_b64 s[18:19], s[6:7]
	s_cbranch_execz .LBB0_908
	s_add_u32 s36, s8, s2
	s_addc_u32 s37, s9, s3
	v_mul_f32_e32 v4, 0x3c010204, v8
	global_store_dword v85, v4, s[36:37]
	s_branch .LBB0_908
